# all six GEMM K-loops: LDS-DMA source addresses as SGPR base + 32-bit lane offset (16 64-bit VALU adds per iteration removed, two +0x80 bases formed with SALU)
# speedup vs baseline: 1.0076x; 1.0008x over previous
; #define PG8_STAGE(bufoff, gbase, voff) do { _Pragma("unroll") for (int _i = 0; _i < 2; ++_i) \
;         __builtin_amdgcn_global_load_lds((const unsigned*)((const char*)(gbase) + (voff)[_i]), (LAS unsigned*)(lds + (bufoff) + ldsw + _i * 8192), 16, 0, 0); } while (0)
; #define PG8_LDA(dst, b, h) do { _Pragma("unroll") for (int m = 0; m < 4; ++m) _Pragma("unroll") for (int k = 0; k < 2; ++k) dst[m][k] = *(const LAS bf16x8*)(lds + PG8_SA(b, h) + aoff + m * 2048 + k * 1024); } while (0)
; #define PG8_LDB(dst, b, h) do { _Pragma("unroll") for (int n = 0; n < 2; ++n) _Pragma("unroll") for (int k = 0; k < 2; ++k) dst[n][k] = *(const LAS bf16x8*)(lds + PG8_SB(b, h) + boff + n * 2048 + k * 1024); } while (0)
; #define PG8_MMA(ai, bj, At, Bt) do { __builtin_amdgcn_s_setprio(1); _Pragma("unroll") for (int m = 0; m < 4; ++m) _Pragma("unroll") for (int n = 0; n < 2; ++n) _Pragma("unroll") for (int k = 0; k < 2; ++k) \
;         acc[ai][bj][m][n] = __builtin_amdgcn_mfma_f32_16x16x32_bf16(Bt[n][k], At[m][k], acc[ai][bj][m][n], 0, 0, 0); __builtin_amdgcn_s_setprio(0); } while (0)
; #define PG8_WAIT_V(n) asm volatile("s_waitcnt vmcnt(" #n ")" ::: "memory")
; #define PG8_WAIT_L(n) asm volatile("s_waitcnt lgkmcnt(" #n ")" ::: "memory")
; #define PG8_BAR __builtin_amdgcn_s_barrier()
; #define PG8_SCHED __builtin_amdgcn_sched_barrier(0)
; template <class Epi>
; __device__ __forceinline__ void gemm_phase(LAS unsigned char* lds, const Gemm g, const StaticOrder& S, const Epi& E, const int wid) {
;     ...
;             PG8_LDB(B0, 0, 0); PG8_LDB(B1, 0, 1); PG8_SCHED; PG8_LDA(At, 0, 0); PG8_STAGE(PG8_SA(1, 1), a1 + hstepA, voffA);
;             PG8_WAIT_V(8); PG8_WAIT_L(0); PG8_BAR; PG8_MMA(0, 0, At, B0); PG8_MMA(0, 1, At, B1); PG8_BAR; PG8_SCHED;
;             PG8_LDA(At, 0, 1); PG8_STAGE(PG8_SB(0, 0), b2, voffB); PG8_STAGE(PG8_SB(0, 1), b2 + hstepB, voffB); PG8_STAGE(PG8_SA(0, 0), a2, voffA);
;             PG8_WAIT_V(8); PG8_WAIT_L(0); PG8_BAR; PG8_MMA(1, 0, At, B0); PG8_MMA(1, 1, At, B1); PG8_BAR; PG8_SCHED;
.LBB0_157:
	ds_read_b128 v[150:153], v157
	ds_read_b128 v[160:163], v157 offset:1024
	ds_read_b128 v[164:167], v157 offset:2048
	ds_read_b128 v[168:171], v157 offset:3072
	ds_read_b128 v[172:175], v158
	ds_read_b128 v[176:179], v158 offset:1024
	ds_read_b128 v[180:183], v158 offset:2048
	ds_read_b128 v[184:187], v158 offset:3072
	s_add_u32 s8, s10, 0x100
	s_addc_u32 s9, s11, 0
	s_cmp_eq_u32 s60, 28
	s_cselect_b32 s59, s51, s9
	s_cselect_b32 s58, s50, s8
	s_cselect_b32 s57, s20, s55
	s_cselect_b32 s56, s21, s49
	s_add_i32 m0, s0, 0xc000
	s_nop 0
	global_load_lds_dwordx4 v142, s[10:11]
	s_add_i32 m0, s0, 0xe000
	s_nop 0
	global_load_lds_dwordx4 v144, s[10:11]
	ds_read_b128 v[188:191], v159
	ds_read_b128 v[192:195], v159 offset:1024
	ds_read_b128 v[196:199], v159 offset:2048
	ds_read_b128 v[200:203], v159 offset:3072
	ds_read_b128 v[204:207], v159 offset:4096
	ds_read_b128 v[208:211], v159 offset:5120
	ds_read_b128 v[212:215], v159 offset:6144
	ds_read_b128 v[216:219], v159 offset:7168
	s_waitcnt vmcnt(8)
	s_waitcnt lgkmcnt(0)
	s_barrier
	s_setprio 1
	s_waitcnt lgkmcnt(0)
	v_mfma_f32_16x16x32_bf16 v[124:127], v[150:153], v[188:191], v[124:127]
	v_mfma_f32_16x16x32_bf16 v[120:123], v[164:167], v[188:191], v[120:123]
	v_mfma_f32_16x16x32_bf16 v[116:119], v[150:153], v[196:199], v[116:119]
	v_mfma_f32_16x16x32_bf16 v[112:115], v[164:167], v[196:199], v[112:115]
	v_mfma_f32_16x16x32_bf16 v[108:111], v[150:153], v[204:207], v[108:111]
	v_mfma_f32_16x16x32_bf16 v[104:107], v[164:167], v[204:207], v[104:107]
	v_mfma_f32_16x16x32_bf16 v[100:103], v[150:153], v[212:215], v[100:103]
	v_mfma_f32_16x16x32_bf16 v[96:99], v[164:167], v[212:215], v[96:99]
	v_mfma_f32_16x16x32_bf16 v[124:127], v[160:163], v[192:195], v[124:127]
	v_mfma_f32_16x16x32_bf16 v[120:123], v[168:171], v[192:195], v[120:123]
	v_mfma_f32_16x16x32_bf16 v[116:119], v[160:163], v[200:203], v[116:119]
	v_mfma_f32_16x16x32_bf16 v[112:115], v[168:171], v[200:203], v[112:115]
	v_mfma_f32_16x16x32_bf16 v[108:111], v[160:163], v[208:211], v[108:111]
	v_mfma_f32_16x16x32_bf16 v[104:107], v[168:171], v[208:211], v[104:107]
	v_mfma_f32_16x16x32_bf16 v[100:103], v[160:163], v[216:219], v[100:103]
	v_mfma_f32_16x16x32_bf16 v[96:99], v[168:171], v[216:219], v[96:99]
	s_setprio 0
	s_setprio 1
	v_mfma_f32_16x16x32_bf16 v[60:63], v[172:175], v[188:191], v[60:63]
	v_mfma_f32_16x16x32_bf16 v[56:59], v[180:183], v[188:191], v[56:59]
	v_mfma_f32_16x16x32_bf16 v[52:55], v[172:175], v[196:199], v[52:55]
	v_mfma_f32_16x16x32_bf16 v[48:51], v[180:183], v[196:199], v[48:51]
	v_mfma_f32_16x16x32_bf16 v[44:47], v[172:175], v[204:207], v[44:47]
	v_mfma_f32_16x16x32_bf16 v[40:43], v[180:183], v[204:207], v[40:43]
	v_mfma_f32_16x16x32_bf16 v[36:39], v[172:175], v[212:215], v[36:39]
	v_mfma_f32_16x16x32_bf16 v[32:35], v[180:183], v[212:215], v[32:35]
	v_mfma_f32_16x16x32_bf16 v[60:63], v[176:179], v[192:195], v[60:63]
	v_mfma_f32_16x16x32_bf16 v[56:59], v[184:187], v[192:195], v[56:59]
	v_mfma_f32_16x16x32_bf16 v[52:55], v[176:179], v[200:203], v[52:55]
	v_mfma_f32_16x16x32_bf16 v[48:51], v[184:187], v[200:203], v[48:51]
	v_mfma_f32_16x16x32_bf16 v[44:47], v[176:179], v[208:211], v[44:47]
	v_mfma_f32_16x16x32_bf16 v[40:43], v[184:187], v[208:211], v[40:43]
	v_mfma_f32_16x16x32_bf16 v[36:39], v[176:179], v[216:219], v[36:39]
	v_mfma_f32_16x16x32_bf16 v[32:35], v[184:187], v[216:219], v[32:35]
	s_setprio 0
	s_barrier
	s_add_i32 s10, s68, s94
	s_mov_b32 m0, s10
	s_nop 0
	global_load_lds_dwordx4 v130, s[56:57]
	s_add_i32 m0, s10, 0x2000
	s_add_u32 s10, s56, 0x80000
	s_addc_u32 s11, s57, 0
	s_add_i32 s24, s69, s94
	global_load_lds_dwordx4 v134, s[56:57]
	s_mov_b32 m0, s24
	s_nop 0
	global_load_lds_dwordx4 v130, s[10:11]
	s_add_i32 m0, s24, 0x2000
	s_nop 0
	global_load_lds_dwordx4 v134, s[10:11]
	s_mov_b32 m0, s0
	s_nop 0
	global_load_lds_dwordx4 v128, s[58:59]
	s_mov_b32 m0, s1
	s_nop 0
	global_load_lds_dwordx4 v132, s[58:59]
	ds_read_b128 v[188:191], v159 offset:16384
	ds_read_b128 v[192:195], v159 offset:17408
	ds_read_b128 v[196:199], v159 offset:18432
	ds_read_b128 v[200:203], v159 offset:19456
	ds_read_b128 v[204:207], v159 offset:20480
	ds_read_b128 v[208:211], v159 offset:21504
	ds_read_b128 v[212:215], v159 offset:22528
	ds_read_b128 v[216:219], v159 offset:23552
	s_waitcnt vmcnt(8)
	s_waitcnt lgkmcnt(0)
	s_barrier
	s_setprio 1
	s_waitcnt lgkmcnt(0)
	v_mfma_f32_16x16x32_bf16 v[92:95], v[150:153], v[188:191], v[92:95]
	v_mfma_f32_16x16x32_bf16 v[88:91], v[164:167], v[188:191], v[88:91]
	v_mfma_f32_16x16x32_bf16 v[84:87], v[150:153], v[196:199], v[84:87]
	v_mfma_f32_16x16x32_bf16 v[80:83], v[164:167], v[196:199], v[80:83]
	v_mfma_f32_16x16x32_bf16 v[76:79], v[150:153], v[204:207], v[76:79]
	v_mfma_f32_16x16x32_bf16 v[72:75], v[164:167], v[204:207], v[72:75]
	v_mfma_f32_16x16x32_bf16 v[68:71], v[150:153], v[212:215], v[68:71]
	v_mfma_f32_16x16x32_bf16 v[64:67], v[164:167], v[212:215], v[64:67]
	v_mfma_f32_16x16x32_bf16 v[92:95], v[160:163], v[192:195], v[92:95]
	v_mfma_f32_16x16x32_bf16 v[88:91], v[168:171], v[192:195], v[88:91]
	v_mfma_f32_16x16x32_bf16 v[84:87], v[160:163], v[200:203], v[84:87]
	v_mfma_f32_16x16x32_bf16 v[80:83], v[168:171], v[200:203], v[80:83]
	v_mfma_f32_16x16x32_bf16 v[76:79], v[160:163], v[208:211], v[76:79]
	v_mfma_f32_16x16x32_bf16 v[72:75], v[168:171], v[208:211], v[72:75]
	v_mfma_f32_16x16x32_bf16 v[68:71], v[160:163], v[216:219], v[68:71]
	v_mfma_f32_16x16x32_bf16 v[64:67], v[168:171], v[216:219], v[64:67]
	s_setprio 0
	s_setprio 1
	v_mfma_f32_16x16x32_bf16 v[28:31], v[172:175], v[188:191], v[28:31]
	v_mfma_f32_16x16x32_bf16 v[24:27], v[180:183], v[188:191], v[24:27]
	v_mfma_f32_16x16x32_bf16 v[20:23], v[172:175], v[196:199], v[20:23]
	v_mfma_f32_16x16x32_bf16 v[16:19], v[180:183], v[196:199], v[16:19]
	v_mfma_f32_16x16x32_bf16 v[12:15], v[172:175], v[204:207], v[12:15]
	v_mfma_f32_16x16x32_bf16 v[8:11], v[180:183], v[204:207], v[8:11]
	v_mfma_f32_16x16x32_bf16 v[4:7], v[172:175], v[212:215], v[4:7]
	v_mfma_f32_16x16x32_bf16 v[0:3], v[180:183], v[212:215], v[0:3]
	v_mfma_f32_16x16x32_bf16 v[28:31], v[176:179], v[192:195], v[28:31]
	v_mfma_f32_16x16x32_bf16 v[24:27], v[184:187], v[192:195], v[24:27]
	v_mfma_f32_16x16x32_bf16 v[20:23], v[176:179], v[200:203], v[20:23]
	v_mfma_f32_16x16x32_bf16 v[16:19], v[184:187], v[200:203], v[16:19]
	v_mfma_f32_16x16x32_bf16 v[12:15], v[176:179], v[208:211], v[12:15]
	v_mfma_f32_16x16x32_bf16 v[8:11], v[184:187], v[208:211], v[8:11]
	v_mfma_f32_16x16x32_bf16 v[4:7], v[176:179], v[216:219], v[4:7]
	v_mfma_f32_16x16x32_bf16 v[0:3], v[184:187], v[216:219], v[0:3]
	s_setprio 0
	s_barrier
; #define PG8_STAGE(bufoff, gbase, voff) do { _Pragma("unroll") for (int _i = 0; _i < 2; ++_i) \
;         __builtin_amdgcn_global_load_lds((const unsigned*)((const char*)(gbase) + (voff)[_i]), (LAS unsigned*)(lds + (bufoff) + ldsw + _i * 8192), 16, 0, 0); } while (0)
; #define PG8_LDA(dst, b, h) do { _Pragma("unroll") for (int m = 0; m < 4; ++m) _Pragma("unroll") for (int k = 0; k < 2; ++k) dst[m][k] = *(const LAS bf16x8*)(lds + PG8_SA(b, h) + aoff + m * 2048 + k * 1024); } while (0)
; #define PG8_LDB(dst, b, h) do { _Pragma("unroll") for (int n = 0; n < 2; ++n) _Pragma("unroll") for (int k = 0; k < 2; ++k) dst[n][k] = *(const LAS bf16x8*)(lds + PG8_SB(b, h) + boff + n * 2048 + k * 1024); } while (0)
; #define PG8_MMA(ai, bj, At, Bt) do { __builtin_amdgcn_s_setprio(1); _Pragma("unroll") for (int m = 0; m < 4; ++m) _Pragma("unroll") for (int n = 0; n < 2; ++n) _Pragma("unroll") for (int k = 0; k < 2; ++k) \
;         acc[ai][bj][m][n] = __builtin_amdgcn_mfma_f32_16x16x32_bf16(Bt[n][k], At[m][k], acc[ai][bj][m][n], 0, 0, 0); __builtin_amdgcn_s_setprio(0); } while (0)
; #define PG8_WAIT_V(n) asm volatile("s_waitcnt vmcnt(" #n ")" ::: "memory")
; #define PG8_WAIT_L(n) asm volatile("s_waitcnt lgkmcnt(" #n ")" ::: "memory")
; #define PG8_BAR __builtin_amdgcn_s_barrier()
; #define PG8_SCHED __builtin_amdgcn_sched_barrier(0)
; template <class Epi>
; __device__ __forceinline__ void gemm_phase(LAS unsigned char* lds, const Gemm g, const StaticOrder& S, const Epi& E, const int wid) {
;     ...
;             PG8_LDB(B0, 1, 0); PG8_LDB(B1, 1, 1); PG8_SCHED; PG8_LDA(At, 1, 0); PG8_STAGE(PG8_SA(0, 1), a2 + hstepA, voffA);
;             PG8_WAIT_V(8); PG8_WAIT_L(0); PG8_BAR; PG8_MMA(0, 0, At, B0); PG8_MMA(0, 1, At, B1); PG8_BAR; PG8_SCHED;
;             PG8_LDA(At, 1, 1); PG8_STAGE(PG8_SB(1, 0), b3, voffB); PG8_STAGE(PG8_SB(1, 1), b3 + hstepB, voffB); PG8_STAGE(PG8_SA(1, 0), a3, voffA);
;             PG8_WAIT_V(8); PG8_WAIT_L(0); PG8_BAR; PG8_MMA(1, 0, At, B0); PG8_MMA(1, 1, At, B1); PG8_BAR; PG8_SCHED;
;         }
	s_add_i32 s24, 0, 0x18000
	v_add_u32_e32 v136, s24, v139
	s_add_i32 s25, 0, 0x1c000
	ds_read_b128 v[150:153], v136
	ds_read_b128 v[160:163], v136 offset:1024
	ds_read_b128 v[164:167], v136 offset:2048
	ds_read_b128 v[168:171], v136 offset:3072
	v_add_u32_e32 v136, s25, v139
	ds_read_b128 v[172:175], v136
	ds_read_b128 v[176:179], v136 offset:1024
	ds_read_b128 v[180:183], v136 offset:2048
	ds_read_b128 v[184:187], v136 offset:3072
	s_add_u32 s10, s58, 0x80000
	s_addc_u32 s11, s59, 0
	s_mov_b32 m0, s15
	s_nop 0
	global_load_lds_dwordx4 v128, s[10:11]
	s_mov_b32 m0, s26
	s_nop 0
	global_load_lds_dwordx4 v132, s[10:11]
	ds_read_b128 v[188:191], v159 offset:32768
	ds_read_b128 v[192:195], v159 offset:33792
	ds_read_b128 v[196:199], v159 offset:34816
	ds_read_b128 v[200:203], v159 offset:35840
	ds_read_b128 v[204:207], v159 offset:36864
	ds_read_b128 v[208:211], v159 offset:37888
	ds_read_b128 v[212:215], v159 offset:38912
	ds_read_b128 v[216:219], v159 offset:39936
	s_waitcnt vmcnt(8)
	s_waitcnt lgkmcnt(0)
	s_barrier
	s_setprio 1
	s_waitcnt lgkmcnt(0)
	v_mfma_f32_16x16x32_bf16 v[124:127], v[150:153], v[188:191], v[124:127]
	v_mfma_f32_16x16x32_bf16 v[120:123], v[164:167], v[188:191], v[120:123]
	v_mfma_f32_16x16x32_bf16 v[116:119], v[150:153], v[196:199], v[116:119]
	v_mfma_f32_16x16x32_bf16 v[112:115], v[164:167], v[196:199], v[112:115]
	v_mfma_f32_16x16x32_bf16 v[108:111], v[150:153], v[204:207], v[108:111]
	v_mfma_f32_16x16x32_bf16 v[104:107], v[164:167], v[204:207], v[104:107]
	v_mfma_f32_16x16x32_bf16 v[100:103], v[150:153], v[212:215], v[100:103]
	v_mfma_f32_16x16x32_bf16 v[96:99], v[164:167], v[212:215], v[96:99]
	v_mfma_f32_16x16x32_bf16 v[124:127], v[160:163], v[192:195], v[124:127]
	v_mfma_f32_16x16x32_bf16 v[120:123], v[168:171], v[192:195], v[120:123]
	v_mfma_f32_16x16x32_bf16 v[116:119], v[160:163], v[200:203], v[116:119]
	v_mfma_f32_16x16x32_bf16 v[112:115], v[168:171], v[200:203], v[112:115]
	v_mfma_f32_16x16x32_bf16 v[108:111], v[160:163], v[208:211], v[108:111]
	v_mfma_f32_16x16x32_bf16 v[104:107], v[168:171], v[208:211], v[104:107]
	v_mfma_f32_16x16x32_bf16 v[100:103], v[160:163], v[216:219], v[100:103]
	v_mfma_f32_16x16x32_bf16 v[96:99], v[168:171], v[216:219], v[96:99]
	s_setprio 0
	s_setprio 1
	v_mfma_f32_16x16x32_bf16 v[60:63], v[172:175], v[188:191], v[60:63]
	v_mfma_f32_16x16x32_bf16 v[56:59], v[180:183], v[188:191], v[56:59]
	v_mfma_f32_16x16x32_bf16 v[52:55], v[172:175], v[196:199], v[52:55]
	v_mfma_f32_16x16x32_bf16 v[48:51], v[180:183], v[196:199], v[48:51]
	v_mfma_f32_16x16x32_bf16 v[44:47], v[172:175], v[204:207], v[44:47]
	v_mfma_f32_16x16x32_bf16 v[40:43], v[180:183], v[204:207], v[40:43]
	v_mfma_f32_16x16x32_bf16 v[36:39], v[172:175], v[212:215], v[36:39]
	v_mfma_f32_16x16x32_bf16 v[32:35], v[180:183], v[212:215], v[32:35]
	v_mfma_f32_16x16x32_bf16 v[60:63], v[176:179], v[192:195], v[60:63]
	v_mfma_f32_16x16x32_bf16 v[56:59], v[184:187], v[192:195], v[56:59]
	v_mfma_f32_16x16x32_bf16 v[52:55], v[176:179], v[200:203], v[52:55]
	v_mfma_f32_16x16x32_bf16 v[48:51], v[184:187], v[200:203], v[48:51]
	v_mfma_f32_16x16x32_bf16 v[44:47], v[176:179], v[208:211], v[44:47]
	v_mfma_f32_16x16x32_bf16 v[40:43], v[184:187], v[208:211], v[40:43]
	v_mfma_f32_16x16x32_bf16 v[36:39], v[176:179], v[216:219], v[36:39]
	v_mfma_f32_16x16x32_bf16 v[32:35], v[184:187], v[216:219], v[32:35]
	s_setprio 0
	s_barrier
	s_add_i32 s10, s24, s94
	s_add_u32 s98, s56, 0x80
	s_addc_u32 s99, s57, 0
	s_mov_b32 m0, s10
	s_nop 0
	global_load_lds_dwordx4 v130, s[98:99]
	s_add_i32 m0, s10, 0x2000
	s_add_u32 s10, s56, 0x80080
	s_addc_u32 s11, s57, 0
	s_add_i32 s24, s25, s94
	global_load_lds_dwordx4 v134, s[98:99]
	s_mov_b32 m0, s24
	s_nop 0
	global_load_lds_dwordx4 v130, s[10:11]
	s_add_i32 m0, s24, 0x2000
	s_nop 0
	global_load_lds_dwordx4 v134, s[10:11]
	s_add_u32 s100, s58, 0x80
	s_addc_u32 s101, s59, 0
	s_mov_b32 m0, s66
	s_nop 0
	global_load_lds_dwordx4 v128, s[100:101]
	s_mov_b32 m0, s67
	s_nop 0
	global_load_lds_dwordx4 v132, s[100:101]
	ds_read_b128 v[188:191], v159 offset:49152
	ds_read_b128 v[192:195], v159 offset:50176
	ds_read_b128 v[196:199], v159 offset:51200
	ds_read_b128 v[200:203], v159 offset:52224
	ds_read_b128 v[204:207], v159 offset:53248
	ds_read_b128 v[208:211], v159 offset:54272
	ds_read_b128 v[212:215], v159 offset:55296
	ds_read_b128 v[216:219], v159 offset:56320
	s_waitcnt vmcnt(8)
	s_waitcnt lgkmcnt(0)
	s_barrier
	s_setprio 1
	s_waitcnt lgkmcnt(0)
	v_mfma_f32_16x16x32_bf16 v[92:95], v[150:153], v[188:191], v[92:95]
	v_mfma_f32_16x16x32_bf16 v[88:91], v[164:167], v[188:191], v[88:91]
	v_mfma_f32_16x16x32_bf16 v[84:87], v[150:153], v[196:199], v[84:87]
	v_mfma_f32_16x16x32_bf16 v[80:83], v[164:167], v[196:199], v[80:83]
	v_mfma_f32_16x16x32_bf16 v[76:79], v[150:153], v[204:207], v[76:79]
	v_mfma_f32_16x16x32_bf16 v[72:75], v[164:167], v[204:207], v[72:75]
	v_mfma_f32_16x16x32_bf16 v[68:71], v[150:153], v[212:215], v[68:71]
	v_mfma_f32_16x16x32_bf16 v[64:67], v[164:167], v[212:215], v[64:67]
	v_mfma_f32_16x16x32_bf16 v[92:95], v[160:163], v[192:195], v[92:95]
	v_mfma_f32_16x16x32_bf16 v[88:91], v[168:171], v[192:195], v[88:91]
	v_mfma_f32_16x16x32_bf16 v[84:87], v[160:163], v[200:203], v[84:87]
	v_mfma_f32_16x16x32_bf16 v[80:83], v[168:171], v[200:203], v[80:83]
	v_mfma_f32_16x16x32_bf16 v[76:79], v[160:163], v[208:211], v[76:79]
	v_mfma_f32_16x16x32_bf16 v[72:75], v[168:171], v[208:211], v[72:75]
	v_mfma_f32_16x16x32_bf16 v[68:71], v[160:163], v[216:219], v[68:71]
	v_mfma_f32_16x16x32_bf16 v[64:67], v[168:171], v[216:219], v[64:67]
	s_setprio 0
	s_setprio 1
	v_mfma_f32_16x16x32_bf16 v[28:31], v[172:175], v[188:191], v[28:31]
	v_mfma_f32_16x16x32_bf16 v[24:27], v[180:183], v[188:191], v[24:27]
	v_mfma_f32_16x16x32_bf16 v[20:23], v[172:175], v[196:199], v[20:23]
	v_mfma_f32_16x16x32_bf16 v[16:19], v[180:183], v[196:199], v[16:19]
	v_mfma_f32_16x16x32_bf16 v[12:15], v[172:175], v[204:207], v[12:15]
	v_mfma_f32_16x16x32_bf16 v[8:11], v[180:183], v[204:207], v[8:11]
	v_mfma_f32_16x16x32_bf16 v[4:7], v[172:175], v[212:215], v[4:7]
	v_mfma_f32_16x16x32_bf16 v[0:3], v[180:183], v[212:215], v[0:3]
	v_mfma_f32_16x16x32_bf16 v[28:31], v[176:179], v[192:195], v[28:31]
	v_mfma_f32_16x16x32_bf16 v[24:27], v[184:187], v[192:195], v[24:27]
	v_mfma_f32_16x16x32_bf16 v[20:23], v[176:179], v[200:203], v[20:23]
	v_mfma_f32_16x16x32_bf16 v[16:19], v[184:187], v[200:203], v[16:19]
	v_mfma_f32_16x16x32_bf16 v[12:15], v[176:179], v[208:211], v[12:15]
	v_mfma_f32_16x16x32_bf16 v[8:11], v[184:187], v[208:211], v[8:11]
	v_mfma_f32_16x16x32_bf16 v[4:7], v[176:179], v[216:219], v[4:7]
	v_mfma_f32_16x16x32_bf16 v[0:3], v[184:187], v[216:219], v[0:3]
	s_setprio 0
	s_barrier
	s_add_i32 s60, s60, 2
	s_add_u32 s49, s49, 0x100
	s_addc_u32 s55, s55, 0
	s_cmp_gt_u32 s60, 29
	s_mov_b64 s[10:11], s[8:9]
	s_cbranch_scc0 .LBB0_157
	s_and_b64 vcc, exec, s[22:23]
	s_cbranch_vccz .LBB0_160
	s_barrier

; #define PG8_STAGE(bufoff, gbase, voff) do { _Pragma("unroll") for (int _i = 0; _i < 2; ++_i) \
;         __builtin_amdgcn_global_load_lds((const unsigned*)((const char*)(gbase) + (voff)[_i]), (LAS unsigned*)(lds + (bufoff) + ldsw + _i * 8192), 16, 0, 0); } while (0)
; #define PG8_LDA(dst, b, h) do { _Pragma("unroll") for (int m = 0; m < 4; ++m) _Pragma("unroll") for (int k = 0; k < 2; ++k) dst[m][k] = *(const LAS bf16x8*)(lds + PG8_SA(b, h) + aoff + m * 2048 + k * 1024); } while (0)
; #define PG8_LDB(dst, b, h) do { _Pragma("unroll") for (int n = 0; n < 2; ++n) _Pragma("unroll") for (int k = 0; k < 2; ++k) dst[n][k] = *(const LAS bf16x8*)(lds + PG8_SB(b, h) + boff + n * 2048 + k * 1024); } while (0)
; #define PG8_MMA(ai, bj, At, Bt) do { __builtin_amdgcn_s_setprio(1); _Pragma("unroll") for (int m = 0; m < 4; ++m) _Pragma("unroll") for (int n = 0; n < 2; ++n) _Pragma("unroll") for (int k = 0; k < 2; ++k) \
;         acc[ai][bj][m][n] = __builtin_amdgcn_mfma_f32_16x16x32_bf16(Bt[n][k], At[m][k], acc[ai][bj][m][n], 0, 0, 0); __builtin_amdgcn_s_setprio(0); } while (0)
; #define PG8_WAIT_V(n) asm volatile("s_waitcnt vmcnt(" #n ")" ::: "memory")
; #define PG8_WAIT_L(n) asm volatile("s_waitcnt lgkmcnt(" #n ")" ::: "memory")
; #define PG8_BAR __builtin_amdgcn_s_barrier()
; #define PG8_SCHED __builtin_amdgcn_sched_barrier(0)
; template <class Epi>
; __device__ __forceinline__ void gemm_phase(LAS unsigned char* lds, const Gemm g, const StaticOrder& S, const Epi& E, const int wid) {
;     ...
;             PG8_LDB(B0, 0, 0); PG8_LDB(B1, 0, 1); PG8_SCHED; PG8_LDA(At, 0, 0); PG8_STAGE(PG8_SA(1, 1), a1 + hstepA, voffA);
;             PG8_WAIT_V(8); PG8_WAIT_L(0); PG8_BAR; PG8_MMA(0, 0, At, B0); PG8_MMA(0, 1, At, B1); PG8_BAR; PG8_SCHED;
;             PG8_LDA(At, 0, 1); PG8_STAGE(PG8_SB(0, 0), b2, voffB); PG8_STAGE(PG8_SB(0, 1), b2 + hstepB, voffB); PG8_STAGE(PG8_SA(0, 0), a2, voffA);
;             PG8_WAIT_V(8); PG8_WAIT_L(0); PG8_BAR; PG8_MMA(1, 0, At, B0); PG8_MMA(1, 1, At, B1); PG8_BAR; PG8_SCHED;
.LBB0_1669:
	ds_read_b128 v[144:147], v157
	ds_read_b128 v[148:151], v157 offset:1024
	ds_read_b128 v[160:163], v157 offset:2048
	ds_read_b128 v[164:167], v157 offset:3072
	ds_read_b128 v[168:171], v158
	ds_read_b128 v[172:175], v158 offset:1024
	ds_read_b128 v[176:179], v158 offset:2048
	ds_read_b128 v[180:183], v158 offset:3072
	s_add_u32 s6, s46, 0x100
	s_addc_u32 s7, s47, 0
	s_cmp_eq_u32 s55, 12
	s_cselect_b32 s51, s43, s7
	s_cselect_b32 s50, s42, s6
	s_cselect_b32 s49, s11, s54
	s_cselect_b32 s48, s21, s53
	s_add_i32 m0, s0, 0xc000
	s_nop 0
	global_load_lds_dwordx4 v136, s[46:47]
	s_add_i32 m0, s0, 0xe000
	s_nop 0
	global_load_lds_dwordx4 v138, s[46:47]
	ds_read_b128 v[184:187], v159
	ds_read_b128 v[188:191], v159 offset:1024
	ds_read_b128 v[192:195], v159 offset:2048
	ds_read_b128 v[196:199], v159 offset:3072
	ds_read_b128 v[200:203], v159 offset:4096
	ds_read_b128 v[204:207], v159 offset:5120
	ds_read_b128 v[208:211], v159 offset:6144
	ds_read_b128 v[212:215], v159 offset:7168
	s_waitcnt vmcnt(8)
	s_waitcnt lgkmcnt(0)
	s_barrier
	s_setprio 1
	s_waitcnt lgkmcnt(0)
	v_mfma_f32_16x16x32_bf16 v[124:127], v[144:147], v[184:187], v[124:127]
	v_mfma_f32_16x16x32_bf16 v[120:123], v[160:163], v[184:187], v[120:123]
	v_mfma_f32_16x16x32_bf16 v[116:119], v[144:147], v[192:195], v[116:119]
	v_mfma_f32_16x16x32_bf16 v[112:115], v[160:163], v[192:195], v[112:115]
	v_mfma_f32_16x16x32_bf16 v[108:111], v[144:147], v[200:203], v[108:111]
	v_mfma_f32_16x16x32_bf16 v[104:107], v[160:163], v[200:203], v[104:107]
	v_mfma_f32_16x16x32_bf16 v[100:103], v[144:147], v[208:211], v[100:103]
	v_mfma_f32_16x16x32_bf16 v[96:99], v[160:163], v[208:211], v[96:99]
	v_mfma_f32_16x16x32_bf16 v[124:127], v[148:151], v[188:191], v[124:127]
	v_mfma_f32_16x16x32_bf16 v[120:123], v[164:167], v[188:191], v[120:123]
	v_mfma_f32_16x16x32_bf16 v[116:119], v[148:151], v[196:199], v[116:119]
	v_mfma_f32_16x16x32_bf16 v[112:115], v[164:167], v[196:199], v[112:115]
	v_mfma_f32_16x16x32_bf16 v[108:111], v[148:151], v[204:207], v[108:111]
	v_mfma_f32_16x16x32_bf16 v[104:107], v[164:167], v[204:207], v[104:107]
	v_mfma_f32_16x16x32_bf16 v[100:103], v[148:151], v[212:215], v[100:103]
	v_mfma_f32_16x16x32_bf16 v[96:99], v[164:167], v[212:215], v[96:99]
	s_setprio 0
	s_setprio 1
	v_mfma_f32_16x16x32_bf16 v[68:71], v[168:171], v[184:187], v[68:71]
	v_mfma_f32_16x16x32_bf16 v[60:63], v[176:179], v[184:187], v[60:63]
	v_mfma_f32_16x16x32_bf16 v[52:55], v[168:171], v[192:195], v[52:55]
	v_mfma_f32_16x16x32_bf16 v[48:51], v[176:179], v[192:195], v[48:51]
	v_mfma_f32_16x16x32_bf16 v[44:47], v[168:171], v[200:203], v[44:47]
	v_mfma_f32_16x16x32_bf16 v[40:43], v[176:179], v[200:203], v[40:43]
	v_mfma_f32_16x16x32_bf16 v[36:39], v[168:171], v[208:211], v[36:39]
	v_mfma_f32_16x16x32_bf16 v[32:35], v[176:179], v[208:211], v[32:35]
	v_mfma_f32_16x16x32_bf16 v[68:71], v[172:175], v[188:191], v[68:71]
	v_mfma_f32_16x16x32_bf16 v[60:63], v[180:183], v[188:191], v[60:63]
	v_mfma_f32_16x16x32_bf16 v[52:55], v[172:175], v[196:199], v[52:55]
	v_mfma_f32_16x16x32_bf16 v[48:51], v[180:183], v[196:199], v[48:51]
	v_mfma_f32_16x16x32_bf16 v[44:47], v[172:175], v[204:207], v[44:47]
	v_mfma_f32_16x16x32_bf16 v[40:43], v[180:183], v[204:207], v[40:43]
	v_mfma_f32_16x16x32_bf16 v[36:39], v[172:175], v[212:215], v[36:39]
	v_mfma_f32_16x16x32_bf16 v[32:35], v[180:183], v[212:215], v[32:35]
	s_setprio 0
	s_barrier
	s_add_i32 s24, s36, s94
	s_mov_b32 m0, s24
	s_nop 0
	global_load_lds_dwordx4 v132, s[48:49]
	s_add_i32 m0, s24, 0x2000
	s_add_u32 s24, s48, 0x40000
	s_addc_u32 s25, s49, 0
	s_add_i32 s46, s37, s94
	global_load_lds_dwordx4 v128, s[48:49]
	s_mov_b32 m0, s46
	s_nop 0
	global_load_lds_dwordx4 v132, s[24:25]
	s_add_i32 m0, s46, 0x2000
	s_nop 0
	global_load_lds_dwordx4 v128, s[24:25]
	s_mov_b32 m0, s0
	s_nop 0
	global_load_lds_dwordx4 v134, s[50:51]
	s_mov_b32 m0, s1
	s_nop 0
	global_load_lds_dwordx4 v130, s[50:51]
	ds_read_b128 v[184:187], v159 offset:16384
	ds_read_b128 v[188:191], v159 offset:17408
	ds_read_b128 v[192:195], v159 offset:18432
	ds_read_b128 v[196:199], v159 offset:19456
	ds_read_b128 v[200:203], v159 offset:20480
	ds_read_b128 v[204:207], v159 offset:21504
	ds_read_b128 v[208:211], v159 offset:22528
	ds_read_b128 v[212:215], v159 offset:23552
	s_waitcnt vmcnt(8)
	s_waitcnt lgkmcnt(0)
	s_barrier
	s_setprio 1
	s_waitcnt lgkmcnt(0)
	v_mfma_f32_16x16x32_bf16 v[92:95], v[144:147], v[184:187], v[92:95]
	v_mfma_f32_16x16x32_bf16 v[88:91], v[160:163], v[184:187], v[88:91]
	v_mfma_f32_16x16x32_bf16 v[84:87], v[144:147], v[192:195], v[84:87]
	v_mfma_f32_16x16x32_bf16 v[80:83], v[160:163], v[192:195], v[80:83]
	v_mfma_f32_16x16x32_bf16 v[76:79], v[144:147], v[200:203], v[76:79]
	v_mfma_f32_16x16x32_bf16 v[72:75], v[160:163], v[200:203], v[72:75]
	v_mfma_f32_16x16x32_bf16 v[64:67], v[144:147], v[208:211], v[64:67]
	v_mfma_f32_16x16x32_bf16 v[56:59], v[160:163], v[208:211], v[56:59]
	v_mfma_f32_16x16x32_bf16 v[92:95], v[148:151], v[188:191], v[92:95]
	v_mfma_f32_16x16x32_bf16 v[88:91], v[164:167], v[188:191], v[88:91]
	v_mfma_f32_16x16x32_bf16 v[84:87], v[148:151], v[196:199], v[84:87]
	v_mfma_f32_16x16x32_bf16 v[80:83], v[164:167], v[196:199], v[80:83]
	v_mfma_f32_16x16x32_bf16 v[76:79], v[148:151], v[204:207], v[76:79]
	v_mfma_f32_16x16x32_bf16 v[72:75], v[164:167], v[204:207], v[72:75]
	v_mfma_f32_16x16x32_bf16 v[64:67], v[148:151], v[212:215], v[64:67]
	v_mfma_f32_16x16x32_bf16 v[56:59], v[164:167], v[212:215], v[56:59]
	s_setprio 0
	s_setprio 1
	v_mfma_f32_16x16x32_bf16 v[28:31], v[168:171], v[184:187], v[28:31]
	v_mfma_f32_16x16x32_bf16 v[24:27], v[176:179], v[184:187], v[24:27]
	v_mfma_f32_16x16x32_bf16 v[20:23], v[168:171], v[192:195], v[20:23]
	v_mfma_f32_16x16x32_bf16 v[16:19], v[176:179], v[192:195], v[16:19]
	v_mfma_f32_16x16x32_bf16 v[12:15], v[168:171], v[200:203], v[12:15]
	v_mfma_f32_16x16x32_bf16 v[8:11], v[176:179], v[200:203], v[8:11]
	v_mfma_f32_16x16x32_bf16 v[4:7], v[168:171], v[208:211], v[4:7]
	v_mfma_f32_16x16x32_bf16 v[0:3], v[176:179], v[208:211], v[0:3]
	v_mfma_f32_16x16x32_bf16 v[28:31], v[172:175], v[188:191], v[28:31]
	v_mfma_f32_16x16x32_bf16 v[24:27], v[180:183], v[188:191], v[24:27]
	v_mfma_f32_16x16x32_bf16 v[20:23], v[172:175], v[196:199], v[20:23]
	v_mfma_f32_16x16x32_bf16 v[16:19], v[180:183], v[196:199], v[16:19]
	v_mfma_f32_16x16x32_bf16 v[12:15], v[172:175], v[204:207], v[12:15]
	v_mfma_f32_16x16x32_bf16 v[8:11], v[180:183], v[204:207], v[8:11]
	v_mfma_f32_16x16x32_bf16 v[4:7], v[172:175], v[212:215], v[4:7]
	v_mfma_f32_16x16x32_bf16 v[0:3], v[180:183], v[212:215], v[0:3]
	s_setprio 0
	s_barrier
; #define PG8_STAGE(bufoff, gbase, voff) do { _Pragma("unroll") for (int _i = 0; _i < 2; ++_i) \
;         __builtin_amdgcn_global_load_lds((const unsigned*)((const char*)(gbase) + (voff)[_i]), (LAS unsigned*)(lds + (bufoff) + ldsw + _i * 8192), 16, 0, 0); } while (0)
; #define PG8_LDA(dst, b, h) do { _Pragma("unroll") for (int m = 0; m < 4; ++m) _Pragma("unroll") for (int k = 0; k < 2; ++k) dst[m][k] = *(const LAS bf16x8*)(lds + PG8_SA(b, h) + aoff + m * 2048 + k * 1024); } while (0)
; #define PG8_LDB(dst, b, h) do { _Pragma("unroll") for (int n = 0; n < 2; ++n) _Pragma("unroll") for (int k = 0; k < 2; ++k) dst[n][k] = *(const LAS bf16x8*)(lds + PG8_SB(b, h) + boff + n * 2048 + k * 1024); } while (0)
; #define PG8_MMA(ai, bj, At, Bt) do { __builtin_amdgcn_s_setprio(1); _Pragma("unroll") for (int m = 0; m < 4; ++m) _Pragma("unroll") for (int n = 0; n < 2; ++n) _Pragma("unroll") for (int k = 0; k < 2; ++k) \
;         acc[ai][bj][m][n] = __builtin_amdgcn_mfma_f32_16x16x32_bf16(Bt[n][k], At[m][k], acc[ai][bj][m][n], 0, 0, 0); __builtin_amdgcn_s_setprio(0); } while (0)
; #define PG8_WAIT_V(n) asm volatile("s_waitcnt vmcnt(" #n ")" ::: "memory")
; #define PG8_WAIT_L(n) asm volatile("s_waitcnt lgkmcnt(" #n ")" ::: "memory")
; #define PG8_BAR __builtin_amdgcn_s_barrier()
; #define PG8_SCHED __builtin_amdgcn_sched_barrier(0)
; template <class Epi>
; __device__ __forceinline__ void gemm_phase(LAS unsigned char* lds, const Gemm g, const StaticOrder& S, const Epi& E, const int wid) {
;     ...
;             PG8_LDB(B0, 1, 0); PG8_LDB(B1, 1, 1); PG8_SCHED; PG8_LDA(At, 1, 0); PG8_STAGE(PG8_SA(0, 1), a2 + hstepA, voffA);
;             PG8_WAIT_V(8); PG8_WAIT_L(0); PG8_BAR; PG8_MMA(0, 0, At, B0); PG8_MMA(0, 1, At, B1); PG8_BAR; PG8_SCHED;
;             PG8_LDA(At, 1, 1); PG8_STAGE(PG8_SB(1, 0), b3, voffB); PG8_STAGE(PG8_SB(1, 1), b3 + hstepB, voffB); PG8_STAGE(PG8_SA(1, 0), a3, voffA);
;             PG8_WAIT_V(8); PG8_WAIT_L(0); PG8_BAR; PG8_MMA(1, 0, At, B0); PG8_MMA(1, 1, At, B1); PG8_BAR; PG8_SCHED;
;         }
	s_add_i32 s46, 0, 0x18000
	s_add_i32 s47, 0, 0x1c000
	v_add_u32_e32 v164, s46, v154
	v_add_u32_e32 v180, s47, v154
	ds_read_b128 v[144:147], v164
	ds_read_b128 v[148:151], v164 offset:1024
	ds_read_b128 v[160:163], v164 offset:2048
	ds_read_b128 v[164:167], v164 offset:3072
	ds_read_b128 v[168:171], v180
	ds_read_b128 v[172:175], v180 offset:1024
	ds_read_b128 v[176:179], v180 offset:2048
	ds_read_b128 v[180:183], v180 offset:3072
	s_add_u32 s24, s50, 0x40000
	s_addc_u32 s25, s51, 0
	s_mov_b32 m0, s15
	s_nop 0
	global_load_lds_dwordx4 v134, s[24:25]
	s_mov_b32 m0, s26
	s_nop 0
	global_load_lds_dwordx4 v130, s[24:25]
	ds_read_b128 v[184:187], v159 offset:32768
	ds_read_b128 v[188:191], v159 offset:33792
	ds_read_b128 v[192:195], v159 offset:34816
	ds_read_b128 v[196:199], v159 offset:35840
	ds_read_b128 v[200:203], v159 offset:36864
	ds_read_b128 v[204:207], v159 offset:37888
	ds_read_b128 v[208:211], v159 offset:38912
	ds_read_b128 v[212:215], v159 offset:39936
	s_waitcnt vmcnt(8)
	s_waitcnt lgkmcnt(0)
	s_barrier
	s_setprio 1
	s_waitcnt lgkmcnt(0)
	v_mfma_f32_16x16x32_bf16 v[124:127], v[144:147], v[184:187], v[124:127]
	v_mfma_f32_16x16x32_bf16 v[120:123], v[160:163], v[184:187], v[120:123]
	v_mfma_f32_16x16x32_bf16 v[116:119], v[144:147], v[192:195], v[116:119]
	v_mfma_f32_16x16x32_bf16 v[112:115], v[160:163], v[192:195], v[112:115]
	v_mfma_f32_16x16x32_bf16 v[108:111], v[144:147], v[200:203], v[108:111]
	v_mfma_f32_16x16x32_bf16 v[104:107], v[160:163], v[200:203], v[104:107]
	v_mfma_f32_16x16x32_bf16 v[100:103], v[144:147], v[208:211], v[100:103]
	v_mfma_f32_16x16x32_bf16 v[96:99], v[160:163], v[208:211], v[96:99]
	v_mfma_f32_16x16x32_bf16 v[124:127], v[148:151], v[188:191], v[124:127]
	v_mfma_f32_16x16x32_bf16 v[120:123], v[164:167], v[188:191], v[120:123]
	v_mfma_f32_16x16x32_bf16 v[116:119], v[148:151], v[196:199], v[116:119]
	v_mfma_f32_16x16x32_bf16 v[112:115], v[164:167], v[196:199], v[112:115]
	v_mfma_f32_16x16x32_bf16 v[108:111], v[148:151], v[204:207], v[108:111]
	v_mfma_f32_16x16x32_bf16 v[104:107], v[164:167], v[204:207], v[104:107]
	v_mfma_f32_16x16x32_bf16 v[100:103], v[148:151], v[212:215], v[100:103]
	v_mfma_f32_16x16x32_bf16 v[96:99], v[164:167], v[212:215], v[96:99]
	s_setprio 0
	s_setprio 1
	v_mfma_f32_16x16x32_bf16 v[68:71], v[168:171], v[184:187], v[68:71]
	v_mfma_f32_16x16x32_bf16 v[60:63], v[176:179], v[184:187], v[60:63]
	v_mfma_f32_16x16x32_bf16 v[52:55], v[168:171], v[192:195], v[52:55]
	v_mfma_f32_16x16x32_bf16 v[48:51], v[176:179], v[192:195], v[48:51]
	v_mfma_f32_16x16x32_bf16 v[44:47], v[168:171], v[200:203], v[44:47]
	v_mfma_f32_16x16x32_bf16 v[40:43], v[176:179], v[200:203], v[40:43]
	v_mfma_f32_16x16x32_bf16 v[36:39], v[168:171], v[208:211], v[36:39]
	v_mfma_f32_16x16x32_bf16 v[32:35], v[176:179], v[208:211], v[32:35]
	v_mfma_f32_16x16x32_bf16 v[68:71], v[172:175], v[188:191], v[68:71]
	v_mfma_f32_16x16x32_bf16 v[60:63], v[180:183], v[188:191], v[60:63]
	v_mfma_f32_16x16x32_bf16 v[52:55], v[172:175], v[196:199], v[52:55]
	v_mfma_f32_16x16x32_bf16 v[48:51], v[180:183], v[196:199], v[48:51]
	v_mfma_f32_16x16x32_bf16 v[44:47], v[172:175], v[204:207], v[44:47]
	v_mfma_f32_16x16x32_bf16 v[40:43], v[180:183], v[204:207], v[40:43]
	v_mfma_f32_16x16x32_bf16 v[36:39], v[172:175], v[212:215], v[36:39]
	v_mfma_f32_16x16x32_bf16 v[32:35], v[180:183], v[212:215], v[32:35]
	s_setprio 0
	s_barrier
	s_add_i32 s24, s46, s94
	s_add_u32 s98, s48, 0x80
	s_addc_u32 s99, s49, 0
	s_mov_b32 m0, s24
	s_nop 0
	global_load_lds_dwordx4 v132, s[98:99]
	s_add_i32 m0, s24, 0x2000
	s_add_u32 s24, s48, 0x40080
	s_addc_u32 s25, s49, 0
	s_add_i32 s46, s47, s94
	global_load_lds_dwordx4 v128, s[98:99]
	s_mov_b32 m0, s46
	s_nop 0
	global_load_lds_dwordx4 v132, s[24:25]
	s_add_i32 m0, s46, 0x2000
	s_nop 0
	global_load_lds_dwordx4 v128, s[24:25]
	s_add_u32 s100, s50, 0x80
	s_addc_u32 s101, s51, 0
	s_mov_b32 m0, s28
	s_nop 0
	global_load_lds_dwordx4 v134, s[100:101]
	s_mov_b32 m0, s29
	s_nop 0
	global_load_lds_dwordx4 v130, s[100:101]
	ds_read_b128 v[184:187], v159 offset:49152
	ds_read_b128 v[188:191], v159 offset:50176
	ds_read_b128 v[192:195], v159 offset:51200
	ds_read_b128 v[196:199], v159 offset:52224
	ds_read_b128 v[200:203], v159 offset:53248
	ds_read_b128 v[204:207], v159 offset:54272
	ds_read_b128 v[208:211], v159 offset:55296
	ds_read_b128 v[212:215], v159 offset:56320
	s_waitcnt vmcnt(8)
	s_waitcnt lgkmcnt(0)
	s_barrier
	s_setprio 1
	s_waitcnt lgkmcnt(0)
	v_mfma_f32_16x16x32_bf16 v[92:95], v[144:147], v[184:187], v[92:95]
	v_mfma_f32_16x16x32_bf16 v[88:91], v[160:163], v[184:187], v[88:91]
	v_mfma_f32_16x16x32_bf16 v[84:87], v[144:147], v[192:195], v[84:87]
	v_mfma_f32_16x16x32_bf16 v[80:83], v[160:163], v[192:195], v[80:83]
	v_mfma_f32_16x16x32_bf16 v[76:79], v[144:147], v[200:203], v[76:79]
	v_mfma_f32_16x16x32_bf16 v[72:75], v[160:163], v[200:203], v[72:75]
	v_mfma_f32_16x16x32_bf16 v[64:67], v[144:147], v[208:211], v[64:67]
	v_mfma_f32_16x16x32_bf16 v[56:59], v[160:163], v[208:211], v[56:59]
	v_mfma_f32_16x16x32_bf16 v[92:95], v[148:151], v[188:191], v[92:95]
	v_mfma_f32_16x16x32_bf16 v[88:91], v[164:167], v[188:191], v[88:91]
	v_mfma_f32_16x16x32_bf16 v[84:87], v[148:151], v[196:199], v[84:87]
	v_mfma_f32_16x16x32_bf16 v[80:83], v[164:167], v[196:199], v[80:83]
	v_mfma_f32_16x16x32_bf16 v[76:79], v[148:151], v[204:207], v[76:79]
	v_mfma_f32_16x16x32_bf16 v[72:75], v[164:167], v[204:207], v[72:75]
	v_mfma_f32_16x16x32_bf16 v[64:67], v[148:151], v[212:215], v[64:67]
	v_mfma_f32_16x16x32_bf16 v[56:59], v[164:167], v[212:215], v[56:59]
	s_setprio 0
	s_setprio 1
	v_mfma_f32_16x16x32_bf16 v[28:31], v[168:171], v[184:187], v[28:31]
	v_mfma_f32_16x16x32_bf16 v[24:27], v[176:179], v[184:187], v[24:27]
	v_mfma_f32_16x16x32_bf16 v[20:23], v[168:171], v[192:195], v[20:23]
	v_mfma_f32_16x16x32_bf16 v[16:19], v[176:179], v[192:195], v[16:19]
	v_mfma_f32_16x16x32_bf16 v[12:15], v[168:171], v[200:203], v[12:15]
	v_mfma_f32_16x16x32_bf16 v[8:11], v[176:179], v[200:203], v[8:11]
	v_mfma_f32_16x16x32_bf16 v[4:7], v[168:171], v[208:211], v[4:7]
	v_mfma_f32_16x16x32_bf16 v[0:3], v[176:179], v[208:211], v[0:3]
	v_mfma_f32_16x16x32_bf16 v[28:31], v[172:175], v[188:191], v[28:31]
	v_mfma_f32_16x16x32_bf16 v[24:27], v[180:183], v[188:191], v[24:27]
	v_mfma_f32_16x16x32_bf16 v[20:23], v[172:175], v[196:199], v[20:23]
	v_mfma_f32_16x16x32_bf16 v[16:19], v[180:183], v[196:199], v[16:19]
	v_mfma_f32_16x16x32_bf16 v[12:15], v[172:175], v[204:207], v[12:15]
	v_mfma_f32_16x16x32_bf16 v[8:11], v[180:183], v[204:207], v[8:11]
	v_mfma_f32_16x16x32_bf16 v[4:7], v[172:175], v[212:215], v[4:7]
	v_mfma_f32_16x16x32_bf16 v[0:3], v[180:183], v[212:215], v[0:3]
	s_setprio 0
	s_barrier
	s_add_i32 s55, s55, 2
	s_add_u32 s53, s53, 0x100
	s_addc_u32 s54, s54, 0
	s_cmp_gt_u32 s55, 13
	s_mov_b64 s[46:47], s[6:7]
	s_cbranch_scc0 .LBB0_1669
	s_and_b64 vcc, exec, s[22:23]
	s_cbranch_vccz .LBB0_1672
	s_barrier

; #define PG8_STAGE(bufoff, gbase, voff) do { _Pragma("unroll") for (int _i = 0; _i < 2; ++_i) \
;         __builtin_amdgcn_global_load_lds((const unsigned*)((const char*)(gbase) + (voff)[_i]), (LAS unsigned*)(lds + (bufoff) + ldsw + _i * 8192), 16, 0, 0); } while (0)
; #define PG8_LDA(dst, b, h) do { _Pragma("unroll") for (int m = 0; m < 4; ++m) _Pragma("unroll") for (int k = 0; k < 2; ++k) dst[m][k] = *(const LAS bf16x8*)(lds + PG8_SA(b, h) + aoff + m * 2048 + k * 1024); } while (0)
; #define PG8_LDB(dst, b, h) do { _Pragma("unroll") for (int n = 0; n < 2; ++n) _Pragma("unroll") for (int k = 0; k < 2; ++k) dst[n][k] = *(const LAS bf16x8*)(lds + PG8_SB(b, h) + boff + n * 2048 + k * 1024); } while (0)
; #define PG8_MMA(ai, bj, At, Bt) do { __builtin_amdgcn_s_setprio(1); _Pragma("unroll") for (int m = 0; m < 4; ++m) _Pragma("unroll") for (int n = 0; n < 2; ++n) _Pragma("unroll") for (int k = 0; k < 2; ++k) \
;         acc[ai][bj][m][n] = __builtin_amdgcn_mfma_f32_16x16x32_bf16(Bt[n][k], At[m][k], acc[ai][bj][m][n], 0, 0, 0); __builtin_amdgcn_s_setprio(0); } while (0)
; #define PG8_WAIT_V(n) asm volatile("s_waitcnt vmcnt(" #n ")" ::: "memory")
; #define PG8_WAIT_L(n) asm volatile("s_waitcnt lgkmcnt(" #n ")" ::: "memory")
; #define PG8_BAR __builtin_amdgcn_s_barrier()
; #define PG8_SCHED __builtin_amdgcn_sched_barrier(0)
; template <class Epi>
; __device__ __forceinline__ void gemm_phase(LAS unsigned char* lds, const Gemm g, const StaticOrder& S, const Epi& E, const int wid) {
;     ...
;             PG8_LDB(B0, 0, 0); PG8_LDB(B1, 0, 1); PG8_SCHED; PG8_LDA(At, 0, 0); PG8_STAGE(PG8_SA(1, 1), a1 + hstepA, voffA);
;             PG8_WAIT_V(8); PG8_WAIT_L(0); PG8_BAR; PG8_MMA(0, 0, At, B0); PG8_MMA(0, 1, At, B1); PG8_BAR; PG8_SCHED;
;             PG8_LDA(At, 0, 1); PG8_STAGE(PG8_SB(0, 0), b2, voffB); PG8_STAGE(PG8_SB(0, 1), b2 + hstepB, voffB); PG8_STAGE(PG8_SA(0, 0), a2, voffA);
;             PG8_WAIT_V(8); PG8_WAIT_L(0); PG8_BAR; PG8_MMA(1, 0, At, B0); PG8_MMA(1, 1, At, B1); PG8_BAR; PG8_SCHED;
.LBB0_1692:
	ds_read_b128 v[144:147], v159
	ds_read_b128 v[148:151], v159 offset:1024
	ds_read_b128 v[152:155], v159 offset:2048
	ds_read_b128 v[162:165], v159 offset:3072
	ds_read_b128 v[166:169], v160
	ds_read_b128 v[170:173], v160 offset:1024
	ds_read_b128 v[174:177], v160 offset:2048
	ds_read_b128 v[178:181], v160 offset:3072
	s_add_u32 s6, s50, 0x100
	s_addc_u32 s7, s51, 0
	s_cmp_eq_u32 s58, 12
	s_cselect_b32 s55, s47, s7
	s_cselect_b32 s54, s46, s6
	s_cselect_b32 s53, s21, s57
	s_cselect_b32 s52, s38, s45
	s_add_i32 m0, s0, 0xc000
	s_nop 0
	global_load_lds_dwordx4 v136, s[50:51]
	s_add_i32 m0, s0, 0xe000
	s_nop 0
	global_load_lds_dwordx4 v138, s[50:51]
	ds_read_b128 v[182:185], v161
	ds_read_b128 v[186:189], v161 offset:1024
	ds_read_b128 v[190:193], v161 offset:2048
	ds_read_b128 v[194:197], v161 offset:3072
	ds_read_b128 v[198:201], v161 offset:4096
	ds_read_b128 v[202:205], v161 offset:5120
	ds_read_b128 v[206:209], v161 offset:6144
	ds_read_b128 v[210:213], v161 offset:7168
	s_waitcnt vmcnt(8)
	s_waitcnt lgkmcnt(0)
	s_barrier
	s_setprio 1
	s_waitcnt lgkmcnt(0)
	v_mfma_f32_16x16x32_bf16 v[124:127], v[144:147], v[182:185], v[124:127]
	v_mfma_f32_16x16x32_bf16 v[120:123], v[152:155], v[182:185], v[120:123]
	v_mfma_f32_16x16x32_bf16 v[116:119], v[144:147], v[190:193], v[116:119]
	v_mfma_f32_16x16x32_bf16 v[112:115], v[152:155], v[190:193], v[112:115]
	v_mfma_f32_16x16x32_bf16 v[108:111], v[144:147], v[198:201], v[108:111]
	v_mfma_f32_16x16x32_bf16 v[104:107], v[152:155], v[198:201], v[104:107]
	v_mfma_f32_16x16x32_bf16 v[100:103], v[144:147], v[206:209], v[100:103]
	v_mfma_f32_16x16x32_bf16 v[96:99], v[152:155], v[206:209], v[96:99]
	v_mfma_f32_16x16x32_bf16 v[124:127], v[148:151], v[186:189], v[124:127]
	v_mfma_f32_16x16x32_bf16 v[120:123], v[162:165], v[186:189], v[120:123]
	v_mfma_f32_16x16x32_bf16 v[116:119], v[148:151], v[194:197], v[116:119]
	v_mfma_f32_16x16x32_bf16 v[112:115], v[162:165], v[194:197], v[112:115]
	v_mfma_f32_16x16x32_bf16 v[108:111], v[148:151], v[202:205], v[108:111]
	v_mfma_f32_16x16x32_bf16 v[104:107], v[162:165], v[202:205], v[104:107]
	v_mfma_f32_16x16x32_bf16 v[100:103], v[148:151], v[210:213], v[100:103]
	v_mfma_f32_16x16x32_bf16 v[96:99], v[162:165], v[210:213], v[96:99]
	s_setprio 0
	s_setprio 1
	v_mfma_f32_16x16x32_bf16 v[60:63], v[166:169], v[182:185], v[60:63]
	v_mfma_f32_16x16x32_bf16 v[56:59], v[174:177], v[182:185], v[56:59]
	v_mfma_f32_16x16x32_bf16 v[52:55], v[166:169], v[190:193], v[52:55]
	v_mfma_f32_16x16x32_bf16 v[48:51], v[174:177], v[190:193], v[48:51]
	v_mfma_f32_16x16x32_bf16 v[44:47], v[166:169], v[198:201], v[44:47]
	v_mfma_f32_16x16x32_bf16 v[40:43], v[174:177], v[198:201], v[40:43]
	v_mfma_f32_16x16x32_bf16 v[36:39], v[166:169], v[206:209], v[36:39]
	v_mfma_f32_16x16x32_bf16 v[32:35], v[174:177], v[206:209], v[32:35]
	v_mfma_f32_16x16x32_bf16 v[60:63], v[170:173], v[186:189], v[60:63]
	v_mfma_f32_16x16x32_bf16 v[56:59], v[178:181], v[186:189], v[56:59]
	v_mfma_f32_16x16x32_bf16 v[52:55], v[170:173], v[194:197], v[52:55]
	v_mfma_f32_16x16x32_bf16 v[48:51], v[178:181], v[194:197], v[48:51]
	v_mfma_f32_16x16x32_bf16 v[44:47], v[170:173], v[202:205], v[44:47]
	v_mfma_f32_16x16x32_bf16 v[40:43], v[178:181], v[202:205], v[40:43]
	v_mfma_f32_16x16x32_bf16 v[36:39], v[170:173], v[210:213], v[36:39]
	v_mfma_f32_16x16x32_bf16 v[32:35], v[178:181], v[210:213], v[32:35]
	s_setprio 0
	s_barrier
	s_add_i32 s24, s34, s94
	s_mov_b32 m0, s24
	s_nop 0
	global_load_lds_dwordx4 v132, s[52:53]
	s_add_i32 m0, s24, 0x2000
	s_add_u32 s24, s52, 0x40000
	s_addc_u32 s25, s53, 0
	s_add_i32 s50, s35, s94
	global_load_lds_dwordx4 v128, s[52:53]
	s_mov_b32 m0, s50
	s_nop 0
	global_load_lds_dwordx4 v132, s[24:25]
	s_add_i32 m0, s50, 0x2000
	s_nop 0
	global_load_lds_dwordx4 v128, s[24:25]
	s_mov_b32 m0, s0
	s_nop 0
	global_load_lds_dwordx4 v134, s[54:55]
	s_mov_b32 m0, s1
	s_nop 0
	global_load_lds_dwordx4 v130, s[54:55]
	ds_read_b128 v[182:185], v161 offset:16384
	ds_read_b128 v[186:189], v161 offset:17408
	ds_read_b128 v[190:193], v161 offset:18432
	ds_read_b128 v[194:197], v161 offset:19456
	ds_read_b128 v[198:201], v161 offset:20480
	ds_read_b128 v[202:205], v161 offset:21504
	ds_read_b128 v[206:209], v161 offset:22528
	ds_read_b128 v[210:213], v161 offset:23552
	s_waitcnt vmcnt(8)
	s_waitcnt lgkmcnt(0)
	s_barrier
	s_setprio 1
	s_waitcnt lgkmcnt(0)
	v_mfma_f32_16x16x32_bf16 v[92:95], v[144:147], v[182:185], v[92:95]
	v_mfma_f32_16x16x32_bf16 v[88:91], v[152:155], v[182:185], v[88:91]
	v_mfma_f32_16x16x32_bf16 v[84:87], v[144:147], v[190:193], v[84:87]
	v_mfma_f32_16x16x32_bf16 v[80:83], v[152:155], v[190:193], v[80:83]
	v_mfma_f32_16x16x32_bf16 v[76:79], v[144:147], v[198:201], v[76:79]
	v_mfma_f32_16x16x32_bf16 v[72:75], v[152:155], v[198:201], v[72:75]
	v_mfma_f32_16x16x32_bf16 v[68:71], v[144:147], v[206:209], v[68:71]
	v_mfma_f32_16x16x32_bf16 v[64:67], v[152:155], v[206:209], v[64:67]
	v_mfma_f32_16x16x32_bf16 v[92:95], v[148:151], v[186:189], v[92:95]
	v_mfma_f32_16x16x32_bf16 v[88:91], v[162:165], v[186:189], v[88:91]
	v_mfma_f32_16x16x32_bf16 v[84:87], v[148:151], v[194:197], v[84:87]
	v_mfma_f32_16x16x32_bf16 v[80:83], v[162:165], v[194:197], v[80:83]
	v_mfma_f32_16x16x32_bf16 v[76:79], v[148:151], v[202:205], v[76:79]
	v_mfma_f32_16x16x32_bf16 v[72:75], v[162:165], v[202:205], v[72:75]
	v_mfma_f32_16x16x32_bf16 v[68:71], v[148:151], v[210:213], v[68:71]
	v_mfma_f32_16x16x32_bf16 v[64:67], v[162:165], v[210:213], v[64:67]
	s_setprio 0
	s_setprio 1
	v_mfma_f32_16x16x32_bf16 v[28:31], v[166:169], v[182:185], v[28:31]
	v_mfma_f32_16x16x32_bf16 v[24:27], v[174:177], v[182:185], v[24:27]
	v_mfma_f32_16x16x32_bf16 v[20:23], v[166:169], v[190:193], v[20:23]
	v_mfma_f32_16x16x32_bf16 v[16:19], v[174:177], v[190:193], v[16:19]
	v_mfma_f32_16x16x32_bf16 v[12:15], v[166:169], v[198:201], v[12:15]
	v_mfma_f32_16x16x32_bf16 v[8:11], v[174:177], v[198:201], v[8:11]
	v_mfma_f32_16x16x32_bf16 v[4:7], v[166:169], v[206:209], v[4:7]
	v_mfma_f32_16x16x32_bf16 v[0:3], v[174:177], v[206:209], v[0:3]
	v_mfma_f32_16x16x32_bf16 v[28:31], v[170:173], v[186:189], v[28:31]
	v_mfma_f32_16x16x32_bf16 v[24:27], v[178:181], v[186:189], v[24:27]
	v_mfma_f32_16x16x32_bf16 v[20:23], v[170:173], v[194:197], v[20:23]
	v_mfma_f32_16x16x32_bf16 v[16:19], v[178:181], v[194:197], v[16:19]
	v_mfma_f32_16x16x32_bf16 v[12:15], v[170:173], v[202:205], v[12:15]
	v_mfma_f32_16x16x32_bf16 v[8:11], v[178:181], v[202:205], v[8:11]
	v_mfma_f32_16x16x32_bf16 v[4:7], v[170:173], v[210:213], v[4:7]
	v_mfma_f32_16x16x32_bf16 v[0:3], v[178:181], v[210:213], v[0:3]
	s_setprio 0
	s_barrier
; #define PG8_STAGE(bufoff, gbase, voff) do { _Pragma("unroll") for (int _i = 0; _i < 2; ++_i) \
;         __builtin_amdgcn_global_load_lds((const unsigned*)((const char*)(gbase) + (voff)[_i]), (LAS unsigned*)(lds + (bufoff) + ldsw + _i * 8192), 16, 0, 0); } while (0)
; #define PG8_LDA(dst, b, h) do { _Pragma("unroll") for (int m = 0; m < 4; ++m) _Pragma("unroll") for (int k = 0; k < 2; ++k) dst[m][k] = *(const LAS bf16x8*)(lds + PG8_SA(b, h) + aoff + m * 2048 + k * 1024); } while (0)
; #define PG8_LDB(dst, b, h) do { _Pragma("unroll") for (int n = 0; n < 2; ++n) _Pragma("unroll") for (int k = 0; k < 2; ++k) dst[n][k] = *(const LAS bf16x8*)(lds + PG8_SB(b, h) + boff + n * 2048 + k * 1024); } while (0)
; #define PG8_MMA(ai, bj, At, Bt) do { __builtin_amdgcn_s_setprio(1); _Pragma("unroll") for (int m = 0; m < 4; ++m) _Pragma("unroll") for (int n = 0; n < 2; ++n) _Pragma("unroll") for (int k = 0; k < 2; ++k) \
;         acc[ai][bj][m][n] = __builtin_amdgcn_mfma_f32_16x16x32_bf16(Bt[n][k], At[m][k], acc[ai][bj][m][n], 0, 0, 0); __builtin_amdgcn_s_setprio(0); } while (0)
; #define PG8_WAIT_V(n) asm volatile("s_waitcnt vmcnt(" #n ")" ::: "memory")
; #define PG8_WAIT_L(n) asm volatile("s_waitcnt lgkmcnt(" #n ")" ::: "memory")
; #define PG8_BAR __builtin_amdgcn_s_barrier()
; #define PG8_SCHED __builtin_amdgcn_sched_barrier(0)
; template <class Epi>
; __device__ __forceinline__ void gemm_phase(LAS unsigned char* lds, const Gemm g, const StaticOrder& S, const Epi& E, const int wid) {
;     ...
;             PG8_LDB(B0, 1, 0); PG8_LDB(B1, 1, 1); PG8_SCHED; PG8_LDA(At, 1, 0); PG8_STAGE(PG8_SA(0, 1), a2 + hstepA, voffA);
;             PG8_WAIT_V(8); PG8_WAIT_L(0); PG8_BAR; PG8_MMA(0, 0, At, B0); PG8_MMA(0, 1, At, B1); PG8_BAR; PG8_SCHED;
;             PG8_LDA(At, 1, 1); PG8_STAGE(PG8_SB(1, 0), b3, voffB); PG8_STAGE(PG8_SB(1, 1), b3 + hstepB, voffB); PG8_STAGE(PG8_SA(1, 0), a3, voffA);
;             PG8_WAIT_V(8); PG8_WAIT_L(0); PG8_BAR; PG8_MMA(1, 0, At, B0); PG8_MMA(1, 1, At, B1); PG8_BAR; PG8_SCHED;
;         }
	s_add_i32 s50, 0, 0x18000
	s_add_i32 s51, 0, 0x1c000
	v_add_u32_e32 v162, s50, v156
	v_add_u32_e32 v178, s51, v156
	ds_read_b128 v[144:147], v162
	ds_read_b128 v[148:151], v162 offset:1024
	ds_read_b128 v[152:155], v162 offset:2048
	ds_read_b128 v[162:165], v162 offset:3072
	ds_read_b128 v[166:169], v178
	ds_read_b128 v[170:173], v178 offset:1024
	ds_read_b128 v[174:177], v178 offset:2048
	ds_read_b128 v[178:181], v178 offset:3072
	s_add_u32 s24, s54, 0x40000
	s_addc_u32 s25, s55, 0
	s_mov_b32 m0, s15
	s_nop 0
	global_load_lds_dwordx4 v134, s[24:25]
	s_mov_b32 m0, s26
	s_nop 0
	global_load_lds_dwordx4 v130, s[24:25]
	ds_read_b128 v[182:185], v161 offset:32768
	ds_read_b128 v[186:189], v161 offset:33792
	ds_read_b128 v[190:193], v161 offset:34816
	ds_read_b128 v[194:197], v161 offset:35840
	ds_read_b128 v[198:201], v161 offset:36864
	ds_read_b128 v[202:205], v161 offset:37888
	ds_read_b128 v[206:209], v161 offset:38912
	ds_read_b128 v[210:213], v161 offset:39936
	s_waitcnt vmcnt(8)
	s_waitcnt lgkmcnt(0)
	s_barrier
	s_setprio 1
	s_waitcnt lgkmcnt(0)
	v_mfma_f32_16x16x32_bf16 v[124:127], v[144:147], v[182:185], v[124:127]
	v_mfma_f32_16x16x32_bf16 v[120:123], v[152:155], v[182:185], v[120:123]
	v_mfma_f32_16x16x32_bf16 v[116:119], v[144:147], v[190:193], v[116:119]
	v_mfma_f32_16x16x32_bf16 v[112:115], v[152:155], v[190:193], v[112:115]
	v_mfma_f32_16x16x32_bf16 v[108:111], v[144:147], v[198:201], v[108:111]
	v_mfma_f32_16x16x32_bf16 v[104:107], v[152:155], v[198:201], v[104:107]
	v_mfma_f32_16x16x32_bf16 v[100:103], v[144:147], v[206:209], v[100:103]
	v_mfma_f32_16x16x32_bf16 v[96:99], v[152:155], v[206:209], v[96:99]
	v_mfma_f32_16x16x32_bf16 v[124:127], v[148:151], v[186:189], v[124:127]
	v_mfma_f32_16x16x32_bf16 v[120:123], v[162:165], v[186:189], v[120:123]
	v_mfma_f32_16x16x32_bf16 v[116:119], v[148:151], v[194:197], v[116:119]
	v_mfma_f32_16x16x32_bf16 v[112:115], v[162:165], v[194:197], v[112:115]
	v_mfma_f32_16x16x32_bf16 v[108:111], v[148:151], v[202:205], v[108:111]
	v_mfma_f32_16x16x32_bf16 v[104:107], v[162:165], v[202:205], v[104:107]
	v_mfma_f32_16x16x32_bf16 v[100:103], v[148:151], v[210:213], v[100:103]
	v_mfma_f32_16x16x32_bf16 v[96:99], v[162:165], v[210:213], v[96:99]
	s_setprio 0
	s_setprio 1
	v_mfma_f32_16x16x32_bf16 v[60:63], v[166:169], v[182:185], v[60:63]
	v_mfma_f32_16x16x32_bf16 v[56:59], v[174:177], v[182:185], v[56:59]
	v_mfma_f32_16x16x32_bf16 v[52:55], v[166:169], v[190:193], v[52:55]
	v_mfma_f32_16x16x32_bf16 v[48:51], v[174:177], v[190:193], v[48:51]
	v_mfma_f32_16x16x32_bf16 v[44:47], v[166:169], v[198:201], v[44:47]
	v_mfma_f32_16x16x32_bf16 v[40:43], v[174:177], v[198:201], v[40:43]
	v_mfma_f32_16x16x32_bf16 v[36:39], v[166:169], v[206:209], v[36:39]
	v_mfma_f32_16x16x32_bf16 v[32:35], v[174:177], v[206:209], v[32:35]
	v_mfma_f32_16x16x32_bf16 v[60:63], v[170:173], v[186:189], v[60:63]
	v_mfma_f32_16x16x32_bf16 v[56:59], v[178:181], v[186:189], v[56:59]
	v_mfma_f32_16x16x32_bf16 v[52:55], v[170:173], v[194:197], v[52:55]
	v_mfma_f32_16x16x32_bf16 v[48:51], v[178:181], v[194:197], v[48:51]
	v_mfma_f32_16x16x32_bf16 v[44:47], v[170:173], v[202:205], v[44:47]
	v_mfma_f32_16x16x32_bf16 v[40:43], v[178:181], v[202:205], v[40:43]
	v_mfma_f32_16x16x32_bf16 v[36:39], v[170:173], v[210:213], v[36:39]
	v_mfma_f32_16x16x32_bf16 v[32:35], v[178:181], v[210:213], v[32:35]
	s_setprio 0
	s_barrier
	s_add_i32 s24, s50, s94
	s_add_u32 s98, s52, 0x80
	s_addc_u32 s99, s53, 0
	s_mov_b32 m0, s24
	s_nop 0
	global_load_lds_dwordx4 v132, s[98:99]
	s_add_i32 m0, s24, 0x2000
	s_add_u32 s24, s52, 0x40080
	s_addc_u32 s25, s53, 0
	s_add_i32 s50, s51, s94
	global_load_lds_dwordx4 v128, s[98:99]
	s_mov_b32 m0, s50
	s_nop 0
	global_load_lds_dwordx4 v132, s[24:25]
	s_add_i32 m0, s50, 0x2000
	s_nop 0
	global_load_lds_dwordx4 v128, s[24:25]
	s_add_u32 s100, s54, 0x80
	s_addc_u32 s101, s55, 0
	s_mov_b32 m0, s28
	s_nop 0
	global_load_lds_dwordx4 v134, s[100:101]
	s_mov_b32 m0, s29
	s_nop 0
	global_load_lds_dwordx4 v130, s[100:101]
	ds_read_b128 v[182:185], v161 offset:49152
	ds_read_b128 v[186:189], v161 offset:50176
	ds_read_b128 v[190:193], v161 offset:51200
	ds_read_b128 v[194:197], v161 offset:52224
	ds_read_b128 v[198:201], v161 offset:53248
	ds_read_b128 v[202:205], v161 offset:54272
	ds_read_b128 v[206:209], v161 offset:55296
	ds_read_b128 v[210:213], v161 offset:56320
	s_waitcnt vmcnt(8)
	s_waitcnt lgkmcnt(0)
	s_barrier
	s_setprio 1
	s_waitcnt lgkmcnt(0)
	v_mfma_f32_16x16x32_bf16 v[92:95], v[144:147], v[182:185], v[92:95]
	v_mfma_f32_16x16x32_bf16 v[88:91], v[152:155], v[182:185], v[88:91]
	v_mfma_f32_16x16x32_bf16 v[84:87], v[144:147], v[190:193], v[84:87]
	v_mfma_f32_16x16x32_bf16 v[80:83], v[152:155], v[190:193], v[80:83]
	v_mfma_f32_16x16x32_bf16 v[76:79], v[144:147], v[198:201], v[76:79]
	v_mfma_f32_16x16x32_bf16 v[72:75], v[152:155], v[198:201], v[72:75]
	v_mfma_f32_16x16x32_bf16 v[68:71], v[144:147], v[206:209], v[68:71]
	v_mfma_f32_16x16x32_bf16 v[64:67], v[152:155], v[206:209], v[64:67]
	v_mfma_f32_16x16x32_bf16 v[92:95], v[148:151], v[186:189], v[92:95]
	v_mfma_f32_16x16x32_bf16 v[88:91], v[162:165], v[186:189], v[88:91]
	v_mfma_f32_16x16x32_bf16 v[84:87], v[148:151], v[194:197], v[84:87]
	v_mfma_f32_16x16x32_bf16 v[80:83], v[162:165], v[194:197], v[80:83]
	v_mfma_f32_16x16x32_bf16 v[76:79], v[148:151], v[202:205], v[76:79]
	v_mfma_f32_16x16x32_bf16 v[72:75], v[162:165], v[202:205], v[72:75]
	v_mfma_f32_16x16x32_bf16 v[68:71], v[148:151], v[210:213], v[68:71]
	v_mfma_f32_16x16x32_bf16 v[64:67], v[162:165], v[210:213], v[64:67]
	s_setprio 0
	s_setprio 1
	v_mfma_f32_16x16x32_bf16 v[28:31], v[166:169], v[182:185], v[28:31]
	v_mfma_f32_16x16x32_bf16 v[24:27], v[174:177], v[182:185], v[24:27]
	v_mfma_f32_16x16x32_bf16 v[20:23], v[166:169], v[190:193], v[20:23]
	v_mfma_f32_16x16x32_bf16 v[16:19], v[174:177], v[190:193], v[16:19]
	v_mfma_f32_16x16x32_bf16 v[12:15], v[166:169], v[198:201], v[12:15]
	v_mfma_f32_16x16x32_bf16 v[8:11], v[174:177], v[198:201], v[8:11]
	v_mfma_f32_16x16x32_bf16 v[4:7], v[166:169], v[206:209], v[4:7]
	v_mfma_f32_16x16x32_bf16 v[0:3], v[174:177], v[206:209], v[0:3]
	v_mfma_f32_16x16x32_bf16 v[28:31], v[170:173], v[186:189], v[28:31]
	v_mfma_f32_16x16x32_bf16 v[24:27], v[178:181], v[186:189], v[24:27]
	v_mfma_f32_16x16x32_bf16 v[20:23], v[170:173], v[194:197], v[20:23]
	v_mfma_f32_16x16x32_bf16 v[16:19], v[178:181], v[194:197], v[16:19]
	v_mfma_f32_16x16x32_bf16 v[12:15], v[170:173], v[202:205], v[12:15]
	v_mfma_f32_16x16x32_bf16 v[8:11], v[178:181], v[202:205], v[8:11]
	v_mfma_f32_16x16x32_bf16 v[4:7], v[170:173], v[210:213], v[4:7]
	v_mfma_f32_16x16x32_bf16 v[0:3], v[178:181], v[210:213], v[0:3]
	s_setprio 0
	s_barrier
	s_add_i32 s58, s58, 2
	s_add_u32 s45, s45, 0x100
	s_addc_u32 s57, s57, 0
	s_cmp_gt_u32 s58, 13
	s_mov_b64 s[50:51], s[6:7]
	s_cbranch_scc0 .LBB0_1692
	s_and_b64 vcc, exec, s[22:23]
	s_cbranch_vccz .LBB0_1695
	s_barrier

; #define PG8_STAGE(bufoff, gbase, voff) do { _Pragma("unroll") for (int _i = 0; _i < 2; ++_i) \
;         __builtin_amdgcn_global_load_lds((const unsigned*)((const char*)(gbase) + (voff)[_i]), (LAS unsigned*)(lds + (bufoff) + ldsw + _i * 8192), 16, 0, 0); } while (0)
; #define PG8_LDA(dst, b, h) do { _Pragma("unroll") for (int m = 0; m < 4; ++m) _Pragma("unroll") for (int k = 0; k < 2; ++k) dst[m][k] = *(const LAS bf16x8*)(lds + PG8_SA(b, h) + aoff + m * 2048 + k * 1024); } while (0)
; #define PG8_LDB(dst, b, h) do { _Pragma("unroll") for (int n = 0; n < 2; ++n) _Pragma("unroll") for (int k = 0; k < 2; ++k) dst[n][k] = *(const LAS bf16x8*)(lds + PG8_SB(b, h) + boff + n * 2048 + k * 1024); } while (0)
; #define PG8_MMA(ai, bj, At, Bt) do { __builtin_amdgcn_s_setprio(1); _Pragma("unroll") for (int m = 0; m < 4; ++m) _Pragma("unroll") for (int n = 0; n < 2; ++n) _Pragma("unroll") for (int k = 0; k < 2; ++k) \
;         acc[ai][bj][m][n] = __builtin_amdgcn_mfma_f32_16x16x32_bf16(Bt[n][k], At[m][k], acc[ai][bj][m][n], 0, 0, 0); __builtin_amdgcn_s_setprio(0); } while (0)
; #define PG8_WAIT_V(n) asm volatile("s_waitcnt vmcnt(" #n ")" ::: "memory")
; #define PG8_WAIT_L(n) asm volatile("s_waitcnt lgkmcnt(" #n ")" ::: "memory")
; #define PG8_BAR __builtin_amdgcn_s_barrier()
; #define PG8_SCHED __builtin_amdgcn_sched_barrier(0)
; template <class Epi>
; __device__ __forceinline__ void gemm_phase(LAS unsigned char* lds, const Gemm g, const StaticOrder& S, const Epi& E, const int wid) {
;     ...
;         for (int t = 0; t < nt; t += 2) {
;             const bool last = (t == nt - 2);
;             const char* a1 = cA + (size_t)(t + 1) * kstep;
;             const char* a2 = last ? nA : cA + (size_t)(t + 2) * kstep; const char* b2 = last ? nB : cB + (size_t)(t + 2) * kstep;
;             const char* a3 = a2 + kstep; const char* b3 = b2 + kstep;
;             PG8_LDB(B0, 0, 0); PG8_LDB(B1, 0, 1); PG8_SCHED; PG8_LDA(At, 0, 0); PG8_STAGE(PG8_SA(1, 1), a1 + hstepA, voffA);
;             PG8_WAIT_V(8); PG8_WAIT_L(0); PG8_BAR; PG8_MMA(0, 0, At, B0); PG8_MMA(0, 1, At, B1); PG8_BAR; PG8_SCHED;
;             PG8_LDA(At, 0, 1); PG8_STAGE(PG8_SB(0, 0), b2, voffB); PG8_STAGE(PG8_SB(0, 1), b2 + hstepB, voffB); PG8_STAGE(PG8_SA(0, 0), a2, voffA);
;             PG8_WAIT_V(8); PG8_WAIT_L(0); PG8_BAR; PG8_MMA(1, 0, At, B0); PG8_MMA(1, 1, At, B1); PG8_BAR; PG8_SCHED;
.LBB0_1727:
	ds_read_b128 v[144:147], v157
	ds_read_b128 v[148:151], v157 offset:1024
	ds_read_b128 v[160:163], v157 offset:2048
	ds_read_b128 v[164:167], v157 offset:3072
	ds_read_b128 v[168:171], v158
	ds_read_b128 v[172:175], v158 offset:1024
	ds_read_b128 v[176:179], v158 offset:2048
	ds_read_b128 v[180:183], v158 offset:3072
	s_add_u32 s6, s46, 0x100
	s_addc_u32 s7, s47, 0
	s_cmp_eq_u32 s54, 28
	s_cselect_b32 s51, s43, s7
	s_cselect_b32 s50, s42, s6
	s_cselect_b32 s49, s21, s53
	s_cselect_b32 s48, s41, s52
	s_add_i32 m0, s1, 0xc000
	s_nop 0
	global_load_lds_dwordx4 v136, s[46:47]
	s_add_i32 m0, s1, 0xe000
	s_nop 0
	global_load_lds_dwordx4 v138, s[46:47]
	ds_read_b128 v[184:187], v159
	ds_read_b128 v[188:191], v159 offset:1024
	ds_read_b128 v[192:195], v159 offset:2048
	ds_read_b128 v[196:199], v159 offset:3072
	ds_read_b128 v[200:203], v159 offset:4096
	ds_read_b128 v[204:207], v159 offset:5120
	ds_read_b128 v[208:211], v159 offset:6144
	ds_read_b128 v[212:215], v159 offset:7168
	s_waitcnt vmcnt(8)
	s_waitcnt lgkmcnt(0)
	s_barrier
	s_setprio 1
	s_waitcnt lgkmcnt(0)
	v_mfma_f32_16x16x32_bf16 v[124:127], v[144:147], v[184:187], v[124:127]
	v_mfma_f32_16x16x32_bf16 v[120:123], v[160:163], v[184:187], v[120:123]
	v_mfma_f32_16x16x32_bf16 v[116:119], v[144:147], v[192:195], v[116:119]
	v_mfma_f32_16x16x32_bf16 v[112:115], v[160:163], v[192:195], v[112:115]
	v_mfma_f32_16x16x32_bf16 v[108:111], v[144:147], v[200:203], v[108:111]
	v_mfma_f32_16x16x32_bf16 v[104:107], v[160:163], v[200:203], v[104:107]
	v_mfma_f32_16x16x32_bf16 v[100:103], v[144:147], v[208:211], v[100:103]
	v_mfma_f32_16x16x32_bf16 v[96:99], v[160:163], v[208:211], v[96:99]
	v_mfma_f32_16x16x32_bf16 v[124:127], v[148:151], v[188:191], v[124:127]
	v_mfma_f32_16x16x32_bf16 v[120:123], v[164:167], v[188:191], v[120:123]
	v_mfma_f32_16x16x32_bf16 v[116:119], v[148:151], v[196:199], v[116:119]
	v_mfma_f32_16x16x32_bf16 v[112:115], v[164:167], v[196:199], v[112:115]
	v_mfma_f32_16x16x32_bf16 v[108:111], v[148:151], v[204:207], v[108:111]
	v_mfma_f32_16x16x32_bf16 v[104:107], v[164:167], v[204:207], v[104:107]
	v_mfma_f32_16x16x32_bf16 v[100:103], v[148:151], v[212:215], v[100:103]
	v_mfma_f32_16x16x32_bf16 v[96:99], v[164:167], v[212:215], v[96:99]
	s_setprio 0
	s_setprio 1
	v_mfma_f32_16x16x32_bf16 v[76:79], v[168:171], v[184:187], v[76:79]
	v_mfma_f32_16x16x32_bf16 v[64:67], v[176:179], v[184:187], v[64:67]
	v_mfma_f32_16x16x32_bf16 v[56:59], v[168:171], v[192:195], v[56:59]
	v_mfma_f32_16x16x32_bf16 v[48:51], v[176:179], v[192:195], v[48:51]
	v_mfma_f32_16x16x32_bf16 v[44:47], v[168:171], v[200:203], v[44:47]
	v_mfma_f32_16x16x32_bf16 v[40:43], v[176:179], v[200:203], v[40:43]
	v_mfma_f32_16x16x32_bf16 v[36:39], v[168:171], v[208:211], v[36:39]
	v_mfma_f32_16x16x32_bf16 v[32:35], v[176:179], v[208:211], v[32:35]
	v_mfma_f32_16x16x32_bf16 v[76:79], v[172:175], v[188:191], v[76:79]
	v_mfma_f32_16x16x32_bf16 v[64:67], v[180:183], v[188:191], v[64:67]
	v_mfma_f32_16x16x32_bf16 v[56:59], v[172:175], v[196:199], v[56:59]
	v_mfma_f32_16x16x32_bf16 v[48:51], v[180:183], v[196:199], v[48:51]
	v_mfma_f32_16x16x32_bf16 v[44:47], v[172:175], v[204:207], v[44:47]
	v_mfma_f32_16x16x32_bf16 v[40:43], v[180:183], v[204:207], v[40:43]
	v_mfma_f32_16x16x32_bf16 v[36:39], v[172:175], v[212:215], v[36:39]
	v_mfma_f32_16x16x32_bf16 v[32:35], v[180:183], v[212:215], v[32:35]
	s_setprio 0
	s_barrier
	s_add_i32 s24, s35, s94
	s_mov_b32 m0, s24
	s_nop 0
	global_load_lds_dwordx4 v132, s[48:49]
	s_add_i32 m0, s24, 0x2000
	s_add_u32 s24, s48, 0x80000
	s_addc_u32 s25, s49, 0
	s_add_i32 s46, s36, s94
	global_load_lds_dwordx4 v128, s[48:49]
	s_mov_b32 m0, s46
	s_nop 0
	global_load_lds_dwordx4 v132, s[24:25]
	s_add_i32 m0, s46, 0x2000
	s_nop 0
	global_load_lds_dwordx4 v128, s[24:25]
	s_mov_b32 m0, s1
	s_nop 0
	global_load_lds_dwordx4 v134, s[50:51]
	s_mov_b32 m0, s15
	s_nop 0
	global_load_lds_dwordx4 v130, s[50:51]
	ds_read_b128 v[184:187], v159 offset:16384
	ds_read_b128 v[188:191], v159 offset:17408
	ds_read_b128 v[192:195], v159 offset:18432
	ds_read_b128 v[196:199], v159 offset:19456
	ds_read_b128 v[200:203], v159 offset:20480
	ds_read_b128 v[204:207], v159 offset:21504
	ds_read_b128 v[208:211], v159 offset:22528
	ds_read_b128 v[212:215], v159 offset:23552
	s_waitcnt vmcnt(8)
	s_waitcnt lgkmcnt(0)
	s_barrier
	s_setprio 1
	s_waitcnt lgkmcnt(0)
	v_mfma_f32_16x16x32_bf16 v[92:95], v[144:147], v[184:187], v[92:95]
	v_mfma_f32_16x16x32_bf16 v[88:91], v[160:163], v[184:187], v[88:91]
	v_mfma_f32_16x16x32_bf16 v[84:87], v[144:147], v[192:195], v[84:87]
	v_mfma_f32_16x16x32_bf16 v[80:83], v[160:163], v[192:195], v[80:83]
	v_mfma_f32_16x16x32_bf16 v[72:75], v[144:147], v[200:203], v[72:75]
	v_mfma_f32_16x16x32_bf16 v[68:71], v[160:163], v[200:203], v[68:71]
	v_mfma_f32_16x16x32_bf16 v[60:63], v[144:147], v[208:211], v[60:63]
	v_mfma_f32_16x16x32_bf16 v[52:55], v[160:163], v[208:211], v[52:55]
	v_mfma_f32_16x16x32_bf16 v[92:95], v[148:151], v[188:191], v[92:95]
	v_mfma_f32_16x16x32_bf16 v[88:91], v[164:167], v[188:191], v[88:91]
	v_mfma_f32_16x16x32_bf16 v[84:87], v[148:151], v[196:199], v[84:87]
	v_mfma_f32_16x16x32_bf16 v[80:83], v[164:167], v[196:199], v[80:83]
	v_mfma_f32_16x16x32_bf16 v[72:75], v[148:151], v[204:207], v[72:75]
	v_mfma_f32_16x16x32_bf16 v[68:71], v[164:167], v[204:207], v[68:71]
	v_mfma_f32_16x16x32_bf16 v[60:63], v[148:151], v[212:215], v[60:63]
	v_mfma_f32_16x16x32_bf16 v[52:55], v[164:167], v[212:215], v[52:55]
	s_setprio 0
	s_setprio 1
	v_mfma_f32_16x16x32_bf16 v[28:31], v[168:171], v[184:187], v[28:31]
	v_mfma_f32_16x16x32_bf16 v[24:27], v[176:179], v[184:187], v[24:27]
	v_mfma_f32_16x16x32_bf16 v[20:23], v[168:171], v[192:195], v[20:23]
	v_mfma_f32_16x16x32_bf16 v[16:19], v[176:179], v[192:195], v[16:19]
	v_mfma_f32_16x16x32_bf16 v[12:15], v[168:171], v[200:203], v[12:15]
	v_mfma_f32_16x16x32_bf16 v[8:11], v[176:179], v[200:203], v[8:11]
	v_mfma_f32_16x16x32_bf16 v[4:7], v[168:171], v[208:211], v[4:7]
	v_mfma_f32_16x16x32_bf16 v[0:3], v[176:179], v[208:211], v[0:3]
	v_mfma_f32_16x16x32_bf16 v[28:31], v[172:175], v[188:191], v[28:31]
	v_mfma_f32_16x16x32_bf16 v[24:27], v[180:183], v[188:191], v[24:27]
	v_mfma_f32_16x16x32_bf16 v[20:23], v[172:175], v[196:199], v[20:23]
	v_mfma_f32_16x16x32_bf16 v[16:19], v[180:183], v[196:199], v[16:19]
	v_mfma_f32_16x16x32_bf16 v[12:15], v[172:175], v[204:207], v[12:15]
	v_mfma_f32_16x16x32_bf16 v[8:11], v[180:183], v[204:207], v[8:11]
	v_mfma_f32_16x16x32_bf16 v[4:7], v[172:175], v[212:215], v[4:7]
	v_mfma_f32_16x16x32_bf16 v[0:3], v[180:183], v[212:215], v[0:3]
	s_setprio 0
	s_barrier
; #define PG8_STAGE(bufoff, gbase, voff) do { _Pragma("unroll") for (int _i = 0; _i < 2; ++_i) \
;         __builtin_amdgcn_global_load_lds((const unsigned*)((const char*)(gbase) + (voff)[_i]), (LAS unsigned*)(lds + (bufoff) + ldsw + _i * 8192), 16, 0, 0); } while (0)
; #define PG8_LDA(dst, b, h) do { _Pragma("unroll") for (int m = 0; m < 4; ++m) _Pragma("unroll") for (int k = 0; k < 2; ++k) dst[m][k] = *(const LAS bf16x8*)(lds + PG8_SA(b, h) + aoff + m * 2048 + k * 1024); } while (0)
; #define PG8_LDB(dst, b, h) do { _Pragma("unroll") for (int n = 0; n < 2; ++n) _Pragma("unroll") for (int k = 0; k < 2; ++k) dst[n][k] = *(const LAS bf16x8*)(lds + PG8_SB(b, h) + boff + n * 2048 + k * 1024); } while (0)
; #define PG8_MMA(ai, bj, At, Bt) do { __builtin_amdgcn_s_setprio(1); _Pragma("unroll") for (int m = 0; m < 4; ++m) _Pragma("unroll") for (int n = 0; n < 2; ++n) _Pragma("unroll") for (int k = 0; k < 2; ++k) \
;         acc[ai][bj][m][n] = __builtin_amdgcn_mfma_f32_16x16x32_bf16(Bt[n][k], At[m][k], acc[ai][bj][m][n], 0, 0, 0); __builtin_amdgcn_s_setprio(0); } while (0)
; #define PG8_WAIT_V(n) asm volatile("s_waitcnt vmcnt(" #n ")" ::: "memory")
; #define PG8_WAIT_L(n) asm volatile("s_waitcnt lgkmcnt(" #n ")" ::: "memory")
; #define PG8_BAR __builtin_amdgcn_s_barrier()
; #define PG8_SCHED __builtin_amdgcn_sched_barrier(0)
; template <class Epi>
; __device__ __forceinline__ void gemm_phase(LAS unsigned char* lds, const Gemm g, const StaticOrder& S, const Epi& E, const int wid) {
;     ...
;             PG8_LDB(B0, 1, 0); PG8_LDB(B1, 1, 1); PG8_SCHED; PG8_LDA(At, 1, 0); PG8_STAGE(PG8_SA(0, 1), a2 + hstepA, voffA);
;             PG8_WAIT_V(8); PG8_WAIT_L(0); PG8_BAR; PG8_MMA(0, 0, At, B0); PG8_MMA(0, 1, At, B1); PG8_BAR; PG8_SCHED;
;             PG8_LDA(At, 1, 1); PG8_STAGE(PG8_SB(1, 0), b3, voffB); PG8_STAGE(PG8_SB(1, 1), b3 + hstepB, voffB); PG8_STAGE(PG8_SA(1, 0), a3, voffA);
;             PG8_WAIT_V(8); PG8_WAIT_L(0); PG8_BAR; PG8_MMA(1, 0, At, B0); PG8_MMA(1, 1, At, B1); PG8_BAR; PG8_SCHED;
;         }
	s_add_i32 s46, 0, 0x18000
	s_add_i32 s47, 0, 0x1c000
	v_add_u32_e32 v164, s46, v154
	v_add_u32_e32 v180, s47, v154
	ds_read_b128 v[144:147], v164
	ds_read_b128 v[148:151], v164 offset:1024
	ds_read_b128 v[160:163], v164 offset:2048
	ds_read_b128 v[164:167], v164 offset:3072
	ds_read_b128 v[168:171], v180
	ds_read_b128 v[172:175], v180 offset:1024
	ds_read_b128 v[176:179], v180 offset:2048
	ds_read_b128 v[180:183], v180 offset:3072
	s_add_u32 s24, s50, 0x80000
	s_addc_u32 s25, s51, 0
	s_mov_b32 m0, s26
	s_nop 0
	global_load_lds_dwordx4 v134, s[24:25]
	s_mov_b32 m0, s27
	s_nop 0
	global_load_lds_dwordx4 v130, s[24:25]
	ds_read_b128 v[184:187], v159 offset:32768
	ds_read_b128 v[188:191], v159 offset:33792
	ds_read_b128 v[192:195], v159 offset:34816
	ds_read_b128 v[196:199], v159 offset:35840
	ds_read_b128 v[200:203], v159 offset:36864
	ds_read_b128 v[204:207], v159 offset:37888
	ds_read_b128 v[208:211], v159 offset:38912
	ds_read_b128 v[212:215], v159 offset:39936
	s_waitcnt vmcnt(8)
	s_waitcnt lgkmcnt(0)
	s_barrier
	s_setprio 1
	s_waitcnt lgkmcnt(0)
	v_mfma_f32_16x16x32_bf16 v[124:127], v[144:147], v[184:187], v[124:127]
	v_mfma_f32_16x16x32_bf16 v[120:123], v[160:163], v[184:187], v[120:123]
	v_mfma_f32_16x16x32_bf16 v[116:119], v[144:147], v[192:195], v[116:119]
	v_mfma_f32_16x16x32_bf16 v[112:115], v[160:163], v[192:195], v[112:115]
	v_mfma_f32_16x16x32_bf16 v[108:111], v[144:147], v[200:203], v[108:111]
	v_mfma_f32_16x16x32_bf16 v[104:107], v[160:163], v[200:203], v[104:107]
	v_mfma_f32_16x16x32_bf16 v[100:103], v[144:147], v[208:211], v[100:103]
	v_mfma_f32_16x16x32_bf16 v[96:99], v[160:163], v[208:211], v[96:99]
	v_mfma_f32_16x16x32_bf16 v[124:127], v[148:151], v[188:191], v[124:127]
	v_mfma_f32_16x16x32_bf16 v[120:123], v[164:167], v[188:191], v[120:123]
	v_mfma_f32_16x16x32_bf16 v[116:119], v[148:151], v[196:199], v[116:119]
	v_mfma_f32_16x16x32_bf16 v[112:115], v[164:167], v[196:199], v[112:115]
	v_mfma_f32_16x16x32_bf16 v[108:111], v[148:151], v[204:207], v[108:111]
	v_mfma_f32_16x16x32_bf16 v[104:107], v[164:167], v[204:207], v[104:107]
	v_mfma_f32_16x16x32_bf16 v[100:103], v[148:151], v[212:215], v[100:103]
	v_mfma_f32_16x16x32_bf16 v[96:99], v[164:167], v[212:215], v[96:99]
	s_setprio 0
	s_setprio 1
	v_mfma_f32_16x16x32_bf16 v[76:79], v[168:171], v[184:187], v[76:79]
	v_mfma_f32_16x16x32_bf16 v[64:67], v[176:179], v[184:187], v[64:67]
	v_mfma_f32_16x16x32_bf16 v[56:59], v[168:171], v[192:195], v[56:59]
	v_mfma_f32_16x16x32_bf16 v[48:51], v[176:179], v[192:195], v[48:51]
	v_mfma_f32_16x16x32_bf16 v[44:47], v[168:171], v[200:203], v[44:47]
	v_mfma_f32_16x16x32_bf16 v[40:43], v[176:179], v[200:203], v[40:43]
	v_mfma_f32_16x16x32_bf16 v[36:39], v[168:171], v[208:211], v[36:39]
	v_mfma_f32_16x16x32_bf16 v[32:35], v[176:179], v[208:211], v[32:35]
	v_mfma_f32_16x16x32_bf16 v[76:79], v[172:175], v[188:191], v[76:79]
	v_mfma_f32_16x16x32_bf16 v[64:67], v[180:183], v[188:191], v[64:67]
	v_mfma_f32_16x16x32_bf16 v[56:59], v[172:175], v[196:199], v[56:59]
	v_mfma_f32_16x16x32_bf16 v[48:51], v[180:183], v[196:199], v[48:51]
	v_mfma_f32_16x16x32_bf16 v[44:47], v[172:175], v[204:207], v[44:47]
	v_mfma_f32_16x16x32_bf16 v[40:43], v[180:183], v[204:207], v[40:43]
	v_mfma_f32_16x16x32_bf16 v[36:39], v[172:175], v[212:215], v[36:39]
	v_mfma_f32_16x16x32_bf16 v[32:35], v[180:183], v[212:215], v[32:35]
	s_setprio 0
	s_barrier
	s_add_i32 s24, s46, s94
	s_add_u32 s98, s48, 0x80
	s_addc_u32 s99, s49, 0
	s_mov_b32 m0, s24
	s_nop 0
	global_load_lds_dwordx4 v132, s[98:99]
	s_add_i32 m0, s24, 0x2000
	s_add_u32 s24, s48, 0x80080
	s_addc_u32 s25, s49, 0
	s_add_i32 s46, s47, s94
	global_load_lds_dwordx4 v128, s[98:99]
	s_mov_b32 m0, s46
	s_nop 0
	global_load_lds_dwordx4 v132, s[24:25]
	s_add_i32 m0, s46, 0x2000
	s_nop 0
	global_load_lds_dwordx4 v128, s[24:25]
	s_add_u32 s100, s50, 0x80
	s_addc_u32 s101, s51, 0
	s_mov_b32 m0, s29
	s_nop 0
	global_load_lds_dwordx4 v134, s[100:101]
	s_mov_b32 m0, s34
	s_nop 0
	global_load_lds_dwordx4 v130, s[100:101]
	ds_read_b128 v[184:187], v159 offset:49152
	ds_read_b128 v[188:191], v159 offset:50176
	ds_read_b128 v[192:195], v159 offset:51200
	ds_read_b128 v[196:199], v159 offset:52224
	ds_read_b128 v[200:203], v159 offset:53248
	ds_read_b128 v[204:207], v159 offset:54272
	ds_read_b128 v[208:211], v159 offset:55296
	ds_read_b128 v[212:215], v159 offset:56320
	s_waitcnt vmcnt(8)
	s_waitcnt lgkmcnt(0)
	s_barrier
	s_setprio 1
	s_waitcnt lgkmcnt(0)
	v_mfma_f32_16x16x32_bf16 v[92:95], v[144:147], v[184:187], v[92:95]
	v_mfma_f32_16x16x32_bf16 v[88:91], v[160:163], v[184:187], v[88:91]
	v_mfma_f32_16x16x32_bf16 v[84:87], v[144:147], v[192:195], v[84:87]
	v_mfma_f32_16x16x32_bf16 v[80:83], v[160:163], v[192:195], v[80:83]
	v_mfma_f32_16x16x32_bf16 v[72:75], v[144:147], v[200:203], v[72:75]
	v_mfma_f32_16x16x32_bf16 v[68:71], v[160:163], v[200:203], v[68:71]
	v_mfma_f32_16x16x32_bf16 v[60:63], v[144:147], v[208:211], v[60:63]
	v_mfma_f32_16x16x32_bf16 v[52:55], v[160:163], v[208:211], v[52:55]
	v_mfma_f32_16x16x32_bf16 v[92:95], v[148:151], v[188:191], v[92:95]
	v_mfma_f32_16x16x32_bf16 v[88:91], v[164:167], v[188:191], v[88:91]
	v_mfma_f32_16x16x32_bf16 v[84:87], v[148:151], v[196:199], v[84:87]
	v_mfma_f32_16x16x32_bf16 v[80:83], v[164:167], v[196:199], v[80:83]
	v_mfma_f32_16x16x32_bf16 v[72:75], v[148:151], v[204:207], v[72:75]
	v_mfma_f32_16x16x32_bf16 v[68:71], v[164:167], v[204:207], v[68:71]
	v_mfma_f32_16x16x32_bf16 v[60:63], v[148:151], v[212:215], v[60:63]
	v_mfma_f32_16x16x32_bf16 v[52:55], v[164:167], v[212:215], v[52:55]
	s_setprio 0
	s_setprio 1
	v_mfma_f32_16x16x32_bf16 v[28:31], v[168:171], v[184:187], v[28:31]
	v_mfma_f32_16x16x32_bf16 v[24:27], v[176:179], v[184:187], v[24:27]
	v_mfma_f32_16x16x32_bf16 v[20:23], v[168:171], v[192:195], v[20:23]
	v_mfma_f32_16x16x32_bf16 v[16:19], v[176:179], v[192:195], v[16:19]
	v_mfma_f32_16x16x32_bf16 v[12:15], v[168:171], v[200:203], v[12:15]
	v_mfma_f32_16x16x32_bf16 v[8:11], v[176:179], v[200:203], v[8:11]
	v_mfma_f32_16x16x32_bf16 v[4:7], v[168:171], v[208:211], v[4:7]
	v_mfma_f32_16x16x32_bf16 v[0:3], v[176:179], v[208:211], v[0:3]
	v_mfma_f32_16x16x32_bf16 v[28:31], v[172:175], v[188:191], v[28:31]
	v_mfma_f32_16x16x32_bf16 v[24:27], v[180:183], v[188:191], v[24:27]
	v_mfma_f32_16x16x32_bf16 v[20:23], v[172:175], v[196:199], v[20:23]
	v_mfma_f32_16x16x32_bf16 v[16:19], v[180:183], v[196:199], v[16:19]
	v_mfma_f32_16x16x32_bf16 v[12:15], v[172:175], v[204:207], v[12:15]
	v_mfma_f32_16x16x32_bf16 v[8:11], v[180:183], v[204:207], v[8:11]
	v_mfma_f32_16x16x32_bf16 v[4:7], v[172:175], v[212:215], v[4:7]
	v_mfma_f32_16x16x32_bf16 v[0:3], v[180:183], v[212:215], v[0:3]
	s_setprio 0
	s_barrier
	s_add_i32 s54, s54, 2
	s_add_u32 s52, s52, 0x100
	s_addc_u32 s53, s53, 0
	s_cmp_gt_u32 s54, 29
	s_mov_b64 s[46:47], s[6:7]
	s_cbranch_scc0 .LBB0_1727
	s_and_b64 vcc, exec, s[22:23]
	s_cbranch_vccz .LBB0_1730
	s_barrier

; #define PG8_STAGE(bufoff, gbase, voff) do { _Pragma("unroll") for (int _i = 0; _i < 2; ++_i) \
;         __builtin_amdgcn_global_load_lds((const unsigned*)((const char*)(gbase) + (voff)[_i]), (LAS unsigned*)(lds + (bufoff) + ldsw + _i * 8192), 16, 0, 0); } while (0)
; #define PG8_LDA(dst, b, h) do { _Pragma("unroll") for (int m = 0; m < 4; ++m) _Pragma("unroll") for (int k = 0; k < 2; ++k) dst[m][k] = *(const LAS bf16x8*)(lds + PG8_SA(b, h) + aoff + m * 2048 + k * 1024); } while (0)
; #define PG8_LDB(dst, b, h) do { _Pragma("unroll") for (int n = 0; n < 2; ++n) _Pragma("unroll") for (int k = 0; k < 2; ++k) dst[n][k] = *(const LAS bf16x8*)(lds + PG8_SB(b, h) + boff + n * 2048 + k * 1024); } while (0)
; #define PG8_MMA(ai, bj, At, Bt) do { __builtin_amdgcn_s_setprio(1); _Pragma("unroll") for (int m = 0; m < 4; ++m) _Pragma("unroll") for (int n = 0; n < 2; ++n) _Pragma("unroll") for (int k = 0; k < 2; ++k) \
;         acc[ai][bj][m][n] = __builtin_amdgcn_mfma_f32_16x16x32_bf16(Bt[n][k], At[m][k], acc[ai][bj][m][n], 0, 0, 0); __builtin_amdgcn_s_setprio(0); } while (0)
; #define PG8_WAIT_V(n) asm volatile("s_waitcnt vmcnt(" #n ")" ::: "memory")
; #define PG8_WAIT_L(n) asm volatile("s_waitcnt lgkmcnt(" #n ")" ::: "memory")
; #define PG8_BAR __builtin_amdgcn_s_barrier()
; #define PG8_SCHED __builtin_amdgcn_sched_barrier(0)
; template <class Epi>
; __device__ __forceinline__ void gemm_phase(LAS unsigned char* lds, const Gemm g, const StaticOrder& S, const Epi& E, const int wid) {
;     ...
;         for (int t = 0; t < nt; t += 2) {
;             const bool last = (t == nt - 2);
;             const char* a1 = cA + (size_t)(t + 1) * kstep;
;             const char* a2 = last ? nA : cA + (size_t)(t + 2) * kstep; const char* b2 = last ? nB : cB + (size_t)(t + 2) * kstep;
;             const char* a3 = a2 + kstep; const char* b3 = b2 + kstep;
;             PG8_LDB(B0, 0, 0); PG8_LDB(B1, 0, 1); PG8_SCHED; PG8_LDA(At, 0, 0); PG8_STAGE(PG8_SA(1, 1), a1 + hstepA, voffA);
;             PG8_WAIT_V(8); PG8_WAIT_L(0); PG8_BAR; PG8_MMA(0, 0, At, B0); PG8_MMA(0, 1, At, B1); PG8_BAR; PG8_SCHED;
;             PG8_LDA(At, 0, 1); PG8_STAGE(PG8_SB(0, 0), b2, voffB); PG8_STAGE(PG8_SB(0, 1), b2 + hstepB, voffB); PG8_STAGE(PG8_SA(0, 0), a2, voffA);
;             PG8_WAIT_V(8); PG8_WAIT_L(0); PG8_BAR; PG8_MMA(1, 0, At, B0); PG8_MMA(1, 1, At, B1); PG8_BAR; PG8_SCHED;
.LBB0_1773:
	ds_read_b128 v[150:153], v147
	ds_read_b128 v[154:157], v147 offset:1024
	ds_read_b128 v[158:161], v147 offset:2048
	ds_read_b128 v[162:165], v147 offset:3072
	ds_read_b128 v[166:169], v148
	ds_read_b128 v[170:173], v148 offset:1024
	ds_read_b128 v[174:177], v148 offset:2048
	ds_read_b128 v[178:181], v148 offset:3072
	s_add_u32 s6, s42, 0x100
	s_addc_u32 s7, s43, 0
	s_cmp_eq_u32 s54, 28
	s_cselect_b32 s47, s21, s7
	s_cselect_b32 s46, s20, s6
	s_cselect_b32 s45, s19, s53
	s_cselect_b32 s44, s51, s52
	s_add_i32 m0, s15, 0xc000
	s_nop 0
	global_load_lds_dwordx4 v136, s[42:43]
	s_add_i32 m0, s15, 0xe000
	s_nop 0
	global_load_lds_dwordx4 v138, s[42:43]
	ds_read_b128 v[182:185], v149
	ds_read_b128 v[186:189], v149 offset:1024
	ds_read_b128 v[190:193], v149 offset:2048
	ds_read_b128 v[194:197], v149 offset:3072
	ds_read_b128 v[198:201], v149 offset:4096
	ds_read_b128 v[202:205], v149 offset:5120
	ds_read_b128 v[206:209], v149 offset:6144
	ds_read_b128 v[210:213], v149 offset:7168
	s_waitcnt vmcnt(8)
	s_waitcnt lgkmcnt(0)
	s_barrier
	s_setprio 1
	s_waitcnt lgkmcnt(0)
	v_mfma_f32_16x16x32_bf16 v[124:127], v[150:153], v[182:185], v[124:127]
	v_mfma_f32_16x16x32_bf16 v[120:123], v[158:161], v[182:185], v[120:123]
	v_mfma_f32_16x16x32_bf16 v[108:111], v[150:153], v[190:193], v[108:111]
	v_mfma_f32_16x16x32_bf16 v[104:107], v[158:161], v[190:193], v[104:107]
	v_mfma_f32_16x16x32_bf16 v[92:95], v[150:153], v[198:201], v[92:95]
	v_mfma_f32_16x16x32_bf16 v[88:91], v[158:161], v[198:201], v[88:91]
	v_mfma_f32_16x16x32_bf16 v[76:79], v[150:153], v[206:209], v[76:79]
	v_mfma_f32_16x16x32_bf16 v[72:75], v[158:161], v[206:209], v[72:75]
	v_mfma_f32_16x16x32_bf16 v[124:127], v[154:157], v[186:189], v[124:127]
	v_mfma_f32_16x16x32_bf16 v[120:123], v[162:165], v[186:189], v[120:123]
	v_mfma_f32_16x16x32_bf16 v[108:111], v[154:157], v[194:197], v[108:111]
	v_mfma_f32_16x16x32_bf16 v[104:107], v[162:165], v[194:197], v[104:107]
	v_mfma_f32_16x16x32_bf16 v[92:95], v[154:157], v[202:205], v[92:95]
	v_mfma_f32_16x16x32_bf16 v[88:91], v[162:165], v[202:205], v[88:91]
	v_mfma_f32_16x16x32_bf16 v[76:79], v[154:157], v[210:213], v[76:79]
	v_mfma_f32_16x16x32_bf16 v[72:75], v[162:165], v[210:213], v[72:75]
	s_setprio 0
	s_setprio 1
	v_mfma_f32_16x16x32_bf16 v[116:119], v[166:169], v[182:185], v[116:119]
	v_mfma_f32_16x16x32_bf16 v[112:115], v[174:177], v[182:185], v[112:115]
	v_mfma_f32_16x16x32_bf16 v[100:103], v[166:169], v[190:193], v[100:103]
	v_mfma_f32_16x16x32_bf16 v[96:99], v[174:177], v[190:193], v[96:99]
	v_mfma_f32_16x16x32_bf16 v[84:87], v[166:169], v[198:201], v[84:87]
	v_mfma_f32_16x16x32_bf16 v[80:83], v[174:177], v[198:201], v[80:83]
	v_mfma_f32_16x16x32_bf16 v[68:71], v[166:169], v[206:209], v[68:71]
	v_mfma_f32_16x16x32_bf16 v[64:67], v[174:177], v[206:209], v[64:67]
	v_mfma_f32_16x16x32_bf16 v[116:119], v[170:173], v[186:189], v[116:119]
	v_mfma_f32_16x16x32_bf16 v[112:115], v[178:181], v[186:189], v[112:115]
	v_mfma_f32_16x16x32_bf16 v[100:103], v[170:173], v[194:197], v[100:103]
	v_mfma_f32_16x16x32_bf16 v[96:99], v[178:181], v[194:197], v[96:99]
	v_mfma_f32_16x16x32_bf16 v[84:87], v[170:173], v[202:205], v[84:87]
	v_mfma_f32_16x16x32_bf16 v[80:83], v[178:181], v[202:205], v[80:83]
	v_mfma_f32_16x16x32_bf16 v[68:71], v[170:173], v[210:213], v[68:71]
	v_mfma_f32_16x16x32_bf16 v[64:67], v[178:181], v[210:213], v[64:67]
	s_setprio 0
	s_barrier
	s_add_i32 s24, s36, s94
	s_mov_b32 m0, s24
	s_nop 0
	global_load_lds_dwordx4 v132, s[44:45]
	s_add_i32 m0, s24, 0x2000
	s_add_u32 s24, s44, 0x80000
	s_addc_u32 s25, s45, 0
	s_add_i32 s42, s37, s94
	global_load_lds_dwordx4 v128, s[44:45]
	s_mov_b32 m0, s42
	s_nop 0
	global_load_lds_dwordx4 v132, s[24:25]
	s_add_i32 m0, s42, 0x2000
	s_nop 0
	global_load_lds_dwordx4 v128, s[24:25]
	s_mov_b32 m0, s15
	s_nop 0
	global_load_lds_dwordx4 v134, s[46:47]
	s_mov_b32 m0, s26
	s_nop 0
	global_load_lds_dwordx4 v130, s[46:47]
	ds_read_b128 v[182:185], v149 offset:16384
	ds_read_b128 v[186:189], v149 offset:17408
	ds_read_b128 v[190:193], v149 offset:18432
	ds_read_b128 v[194:197], v149 offset:19456
	ds_read_b128 v[198:201], v149 offset:20480
	ds_read_b128 v[202:205], v149 offset:21504
	ds_read_b128 v[206:209], v149 offset:22528
	ds_read_b128 v[210:213], v149 offset:23552
	s_waitcnt vmcnt(8)
	s_waitcnt lgkmcnt(0)
	s_barrier
	s_setprio 1
	s_waitcnt lgkmcnt(0)
	v_mfma_f32_16x16x32_bf16 v[60:63], v[150:153], v[182:185], v[60:63]
	v_mfma_f32_16x16x32_bf16 v[56:59], v[158:161], v[182:185], v[56:59]
	v_mfma_f32_16x16x32_bf16 v[44:47], v[150:153], v[190:193], v[44:47]
	v_mfma_f32_16x16x32_bf16 v[40:43], v[158:161], v[190:193], v[40:43]
	v_mfma_f32_16x16x32_bf16 v[28:31], v[150:153], v[198:201], v[28:31]
	v_mfma_f32_16x16x32_bf16 v[24:27], v[158:161], v[198:201], v[24:27]
	v_mfma_f32_16x16x32_bf16 v[12:15], v[150:153], v[206:209], v[12:15]
	v_mfma_f32_16x16x32_bf16 v[8:11], v[158:161], v[206:209], v[8:11]
	v_mfma_f32_16x16x32_bf16 v[60:63], v[154:157], v[186:189], v[60:63]
	v_mfma_f32_16x16x32_bf16 v[56:59], v[162:165], v[186:189], v[56:59]
	v_mfma_f32_16x16x32_bf16 v[44:47], v[154:157], v[194:197], v[44:47]
	v_mfma_f32_16x16x32_bf16 v[40:43], v[162:165], v[194:197], v[40:43]
	v_mfma_f32_16x16x32_bf16 v[28:31], v[154:157], v[202:205], v[28:31]
	v_mfma_f32_16x16x32_bf16 v[24:27], v[162:165], v[202:205], v[24:27]
	v_mfma_f32_16x16x32_bf16 v[12:15], v[154:157], v[210:213], v[12:15]
	v_mfma_f32_16x16x32_bf16 v[8:11], v[162:165], v[210:213], v[8:11]
	s_setprio 0
	s_setprio 1
	v_mfma_f32_16x16x32_bf16 v[52:55], v[166:169], v[182:185], v[52:55]
	v_mfma_f32_16x16x32_bf16 v[48:51], v[174:177], v[182:185], v[48:51]
	v_mfma_f32_16x16x32_bf16 v[36:39], v[166:169], v[190:193], v[36:39]
	v_mfma_f32_16x16x32_bf16 v[32:35], v[174:177], v[190:193], v[32:35]
	v_mfma_f32_16x16x32_bf16 v[20:23], v[166:169], v[198:201], v[20:23]
	v_mfma_f32_16x16x32_bf16 v[16:19], v[174:177], v[198:201], v[16:19]
	v_mfma_f32_16x16x32_bf16 v[4:7], v[166:169], v[206:209], v[4:7]
	v_mfma_f32_16x16x32_bf16 v[0:3], v[174:177], v[206:209], v[0:3]
	v_mfma_f32_16x16x32_bf16 v[52:55], v[170:173], v[186:189], v[52:55]
	v_mfma_f32_16x16x32_bf16 v[48:51], v[178:181], v[186:189], v[48:51]
	v_mfma_f32_16x16x32_bf16 v[36:39], v[170:173], v[194:197], v[36:39]
	v_mfma_f32_16x16x32_bf16 v[32:35], v[178:181], v[194:197], v[32:35]
	v_mfma_f32_16x16x32_bf16 v[20:23], v[170:173], v[202:205], v[20:23]
	v_mfma_f32_16x16x32_bf16 v[16:19], v[178:181], v[202:205], v[16:19]
	v_mfma_f32_16x16x32_bf16 v[4:7], v[170:173], v[210:213], v[4:7]
	v_mfma_f32_16x16x32_bf16 v[0:3], v[178:181], v[210:213], v[0:3]
	s_setprio 0
	s_barrier
; #define PG8_STAGE(bufoff, gbase, voff) do { _Pragma("unroll") for (int _i = 0; _i < 2; ++_i) \
;         __builtin_amdgcn_global_load_lds((const unsigned*)((const char*)(gbase) + (voff)[_i]), (LAS unsigned*)(lds + (bufoff) + ldsw + _i * 8192), 16, 0, 0); } while (0)
; #define PG8_LDA(dst, b, h) do { _Pragma("unroll") for (int m = 0; m < 4; ++m) _Pragma("unroll") for (int k = 0; k < 2; ++k) dst[m][k] = *(const LAS bf16x8*)(lds + PG8_SA(b, h) + aoff + m * 2048 + k * 1024); } while (0)
; #define PG8_LDB(dst, b, h) do { _Pragma("unroll") for (int n = 0; n < 2; ++n) _Pragma("unroll") for (int k = 0; k < 2; ++k) dst[n][k] = *(const LAS bf16x8*)(lds + PG8_SB(b, h) + boff + n * 2048 + k * 1024); } while (0)
; #define PG8_MMA(ai, bj, At, Bt) do { __builtin_amdgcn_s_setprio(1); _Pragma("unroll") for (int m = 0; m < 4; ++m) _Pragma("unroll") for (int n = 0; n < 2; ++n) _Pragma("unroll") for (int k = 0; k < 2; ++k) \
;         acc[ai][bj][m][n] = __builtin_amdgcn_mfma_f32_16x16x32_bf16(Bt[n][k], At[m][k], acc[ai][bj][m][n], 0, 0, 0); __builtin_amdgcn_s_setprio(0); } while (0)
; #define PG8_WAIT_V(n) asm volatile("s_waitcnt vmcnt(" #n ")" ::: "memory")
; #define PG8_WAIT_L(n) asm volatile("s_waitcnt lgkmcnt(" #n ")" ::: "memory")
; #define PG8_BAR __builtin_amdgcn_s_barrier()
; #define PG8_SCHED __builtin_amdgcn_sched_barrier(0)
; template <class Epi>
; __device__ __forceinline__ void gemm_phase(LAS unsigned char* lds, const Gemm g, const StaticOrder& S, const Epi& E, const int wid) {
;     ...
;             PG8_LDB(B0, 1, 0); PG8_LDB(B1, 1, 1); PG8_SCHED; PG8_LDA(At, 1, 0); PG8_STAGE(PG8_SA(0, 1), a2 + hstepA, voffA);
;             PG8_WAIT_V(8); PG8_WAIT_L(0); PG8_BAR; PG8_MMA(0, 0, At, B0); PG8_MMA(0, 1, At, B1); PG8_BAR; PG8_SCHED;
;             PG8_LDA(At, 1, 1); PG8_STAGE(PG8_SB(1, 0), b3, voffB); PG8_STAGE(PG8_SB(1, 1), b3 + hstepB, voffB); PG8_STAGE(PG8_SA(1, 0), a3, voffA);
;             PG8_WAIT_V(8); PG8_WAIT_L(0); PG8_BAR; PG8_MMA(1, 0, At, B0); PG8_MMA(1, 1, At, B1); PG8_BAR; PG8_SCHED;
;         }
	s_add_i32 s42, 0, 0x18000
	s_add_i32 s43, 0, 0x1c000
	v_add_u32_e32 v162, s42, v144
	v_add_u32_e32 v178, s43, v144
	ds_read_b128 v[150:153], v162
	ds_read_b128 v[154:157], v162 offset:1024
	ds_read_b128 v[158:161], v162 offset:2048
	ds_read_b128 v[162:165], v162 offset:3072
	ds_read_b128 v[166:169], v178
	ds_read_b128 v[170:173], v178 offset:1024
	ds_read_b128 v[174:177], v178 offset:2048
	ds_read_b128 v[178:181], v178 offset:3072
	s_add_u32 s24, s46, 0x80000
	s_addc_u32 s25, s47, 0
	s_mov_b32 m0, s27
	s_nop 0
	global_load_lds_dwordx4 v134, s[24:25]
	s_mov_b32 m0, s28
	s_nop 0
	global_load_lds_dwordx4 v130, s[24:25]
	ds_read_b128 v[182:185], v149 offset:32768
	ds_read_b128 v[186:189], v149 offset:33792
	ds_read_b128 v[190:193], v149 offset:34816
	ds_read_b128 v[194:197], v149 offset:35840
	ds_read_b128 v[198:201], v149 offset:36864
	ds_read_b128 v[202:205], v149 offset:37888
	ds_read_b128 v[206:209], v149 offset:38912
	ds_read_b128 v[210:213], v149 offset:39936
	s_waitcnt vmcnt(8)
	s_waitcnt lgkmcnt(0)
	s_barrier
	s_setprio 1
	s_waitcnt lgkmcnt(0)
	v_mfma_f32_16x16x32_bf16 v[124:127], v[150:153], v[182:185], v[124:127]
	v_mfma_f32_16x16x32_bf16 v[120:123], v[158:161], v[182:185], v[120:123]
	v_mfma_f32_16x16x32_bf16 v[108:111], v[150:153], v[190:193], v[108:111]
	v_mfma_f32_16x16x32_bf16 v[104:107], v[158:161], v[190:193], v[104:107]
	v_mfma_f32_16x16x32_bf16 v[92:95], v[150:153], v[198:201], v[92:95]
	v_mfma_f32_16x16x32_bf16 v[88:91], v[158:161], v[198:201], v[88:91]
	v_mfma_f32_16x16x32_bf16 v[76:79], v[150:153], v[206:209], v[76:79]
	v_mfma_f32_16x16x32_bf16 v[72:75], v[158:161], v[206:209], v[72:75]
	v_mfma_f32_16x16x32_bf16 v[124:127], v[154:157], v[186:189], v[124:127]
	v_mfma_f32_16x16x32_bf16 v[120:123], v[162:165], v[186:189], v[120:123]
	v_mfma_f32_16x16x32_bf16 v[108:111], v[154:157], v[194:197], v[108:111]
	v_mfma_f32_16x16x32_bf16 v[104:107], v[162:165], v[194:197], v[104:107]
	v_mfma_f32_16x16x32_bf16 v[92:95], v[154:157], v[202:205], v[92:95]
	v_mfma_f32_16x16x32_bf16 v[88:91], v[162:165], v[202:205], v[88:91]
	v_mfma_f32_16x16x32_bf16 v[76:79], v[154:157], v[210:213], v[76:79]
	v_mfma_f32_16x16x32_bf16 v[72:75], v[162:165], v[210:213], v[72:75]
	s_setprio 0
	s_setprio 1
	v_mfma_f32_16x16x32_bf16 v[116:119], v[166:169], v[182:185], v[116:119]
	v_mfma_f32_16x16x32_bf16 v[112:115], v[174:177], v[182:185], v[112:115]
	v_mfma_f32_16x16x32_bf16 v[100:103], v[166:169], v[190:193], v[100:103]
	v_mfma_f32_16x16x32_bf16 v[96:99], v[174:177], v[190:193], v[96:99]
	v_mfma_f32_16x16x32_bf16 v[84:87], v[166:169], v[198:201], v[84:87]
	v_mfma_f32_16x16x32_bf16 v[80:83], v[174:177], v[198:201], v[80:83]
	v_mfma_f32_16x16x32_bf16 v[68:71], v[166:169], v[206:209], v[68:71]
	v_mfma_f32_16x16x32_bf16 v[64:67], v[174:177], v[206:209], v[64:67]
	v_mfma_f32_16x16x32_bf16 v[116:119], v[170:173], v[186:189], v[116:119]
	v_mfma_f32_16x16x32_bf16 v[112:115], v[178:181], v[186:189], v[112:115]
	v_mfma_f32_16x16x32_bf16 v[100:103], v[170:173], v[194:197], v[100:103]
	v_mfma_f32_16x16x32_bf16 v[96:99], v[178:181], v[194:197], v[96:99]
	v_mfma_f32_16x16x32_bf16 v[84:87], v[170:173], v[202:205], v[84:87]
	v_mfma_f32_16x16x32_bf16 v[80:83], v[178:181], v[202:205], v[80:83]
	v_mfma_f32_16x16x32_bf16 v[68:71], v[170:173], v[210:213], v[68:71]
	v_mfma_f32_16x16x32_bf16 v[64:67], v[178:181], v[210:213], v[64:67]
	s_setprio 0
	s_barrier
	s_add_i32 s24, s42, s94
	s_add_u32 s98, s44, 0x80
	s_addc_u32 s99, s45, 0
	s_mov_b32 m0, s24
	s_nop 0
	global_load_lds_dwordx4 v132, s[98:99]
	s_add_i32 m0, s24, 0x2000
	s_add_u32 s24, s44, 0x80080
	s_addc_u32 s25, s45, 0
	s_add_i32 s42, s43, s94
	global_load_lds_dwordx4 v128, s[98:99]
	s_mov_b32 m0, s42
	s_nop 0
	global_load_lds_dwordx4 v132, s[24:25]
	s_add_i32 m0, s42, 0x2000
	s_nop 0
	global_load_lds_dwordx4 v128, s[24:25]
	s_add_u32 s100, s46, 0x80
	s_addc_u32 s101, s47, 0
	s_mov_b32 m0, s34
	s_nop 0
	global_load_lds_dwordx4 v134, s[100:101]
	s_mov_b32 m0, s35
	s_nop 0
	global_load_lds_dwordx4 v130, s[100:101]
	ds_read_b128 v[182:185], v149 offset:49152
	ds_read_b128 v[186:189], v149 offset:50176
	ds_read_b128 v[190:193], v149 offset:51200
	ds_read_b128 v[194:197], v149 offset:52224
	ds_read_b128 v[198:201], v149 offset:53248
	ds_read_b128 v[202:205], v149 offset:54272
	ds_read_b128 v[206:209], v149 offset:55296
	ds_read_b128 v[210:213], v149 offset:56320
	s_waitcnt vmcnt(8)
	s_waitcnt lgkmcnt(0)
	s_barrier
	s_setprio 1
	s_waitcnt lgkmcnt(0)
	v_mfma_f32_16x16x32_bf16 v[60:63], v[150:153], v[182:185], v[60:63]
	v_mfma_f32_16x16x32_bf16 v[56:59], v[158:161], v[182:185], v[56:59]
	v_mfma_f32_16x16x32_bf16 v[44:47], v[150:153], v[190:193], v[44:47]
	v_mfma_f32_16x16x32_bf16 v[40:43], v[158:161], v[190:193], v[40:43]
	v_mfma_f32_16x16x32_bf16 v[28:31], v[150:153], v[198:201], v[28:31]
	v_mfma_f32_16x16x32_bf16 v[24:27], v[158:161], v[198:201], v[24:27]
	v_mfma_f32_16x16x32_bf16 v[12:15], v[150:153], v[206:209], v[12:15]
	v_mfma_f32_16x16x32_bf16 v[8:11], v[158:161], v[206:209], v[8:11]
	v_mfma_f32_16x16x32_bf16 v[60:63], v[154:157], v[186:189], v[60:63]
	v_mfma_f32_16x16x32_bf16 v[56:59], v[162:165], v[186:189], v[56:59]
	v_mfma_f32_16x16x32_bf16 v[44:47], v[154:157], v[194:197], v[44:47]
	v_mfma_f32_16x16x32_bf16 v[40:43], v[162:165], v[194:197], v[40:43]
	v_mfma_f32_16x16x32_bf16 v[28:31], v[154:157], v[202:205], v[28:31]
	v_mfma_f32_16x16x32_bf16 v[24:27], v[162:165], v[202:205], v[24:27]
	v_mfma_f32_16x16x32_bf16 v[12:15], v[154:157], v[210:213], v[12:15]
	v_mfma_f32_16x16x32_bf16 v[8:11], v[162:165], v[210:213], v[8:11]
	s_setprio 0
	s_setprio 1
	v_mfma_f32_16x16x32_bf16 v[52:55], v[166:169], v[182:185], v[52:55]
	v_mfma_f32_16x16x32_bf16 v[48:51], v[174:177], v[182:185], v[48:51]
	v_mfma_f32_16x16x32_bf16 v[36:39], v[166:169], v[190:193], v[36:39]
	v_mfma_f32_16x16x32_bf16 v[32:35], v[174:177], v[190:193], v[32:35]
	v_mfma_f32_16x16x32_bf16 v[20:23], v[166:169], v[198:201], v[20:23]
	v_mfma_f32_16x16x32_bf16 v[16:19], v[174:177], v[198:201], v[16:19]
	v_mfma_f32_16x16x32_bf16 v[4:7], v[166:169], v[206:209], v[4:7]
	v_mfma_f32_16x16x32_bf16 v[0:3], v[174:177], v[206:209], v[0:3]
	v_mfma_f32_16x16x32_bf16 v[52:55], v[170:173], v[186:189], v[52:55]
	v_mfma_f32_16x16x32_bf16 v[48:51], v[178:181], v[186:189], v[48:51]
	v_mfma_f32_16x16x32_bf16 v[36:39], v[170:173], v[194:197], v[36:39]
	v_mfma_f32_16x16x32_bf16 v[32:35], v[178:181], v[194:197], v[32:35]
	v_mfma_f32_16x16x32_bf16 v[20:23], v[170:173], v[202:205], v[20:23]
	v_mfma_f32_16x16x32_bf16 v[16:19], v[178:181], v[202:205], v[16:19]
	v_mfma_f32_16x16x32_bf16 v[4:7], v[170:173], v[210:213], v[4:7]
	v_mfma_f32_16x16x32_bf16 v[0:3], v[178:181], v[210:213], v[0:3]
	s_setprio 0
	s_barrier
	s_add_i32 s54, s54, 2
	s_add_u32 s52, s52, 0x100
	s_addc_u32 s53, s53, 0
	s_cmp_gt_u32 s54, 29
	s_mov_b64 s[42:43], s[6:7]
	s_cbranch_scc0 .LBB0_1773
	s_and_b64 vcc, exec, s[22:23]
	s_cbranch_vccz .LBB0_1776
	s_barrier

; #define PG8_STAGE(bufoff, gbase, voff) do { _Pragma("unroll") for (int _i = 0; _i < 2; ++_i) \
;         __builtin_amdgcn_global_load_lds((const unsigned*)((const char*)(gbase) + (voff)[_i]), (LAS unsigned*)(lds + (bufoff) + ldsw + _i * 8192), 16, 0, 0); } while (0)
; #define PG8_LDA(dst, b, h) do { _Pragma("unroll") for (int m = 0; m < 4; ++m) _Pragma("unroll") for (int k = 0; k < 2; ++k) dst[m][k] = *(const LAS bf16x8*)(lds + PG8_SA(b, h) + aoff + m * 2048 + k * 1024); } while (0)
; #define PG8_LDB(dst, b, h) do { _Pragma("unroll") for (int n = 0; n < 2; ++n) _Pragma("unroll") for (int k = 0; k < 2; ++k) dst[n][k] = *(const LAS bf16x8*)(lds + PG8_SB(b, h) + boff + n * 2048 + k * 1024); } while (0)
; #define PG8_MMA(ai, bj, At, Bt) do { __builtin_amdgcn_s_setprio(1); _Pragma("unroll") for (int m = 0; m < 4; ++m) _Pragma("unroll") for (int n = 0; n < 2; ++n) _Pragma("unroll") for (int k = 0; k < 2; ++k) \
;         acc[ai][bj][m][n] = __builtin_amdgcn_mfma_f32_16x16x32_bf16(Bt[n][k], At[m][k], acc[ai][bj][m][n], 0, 0, 0); __builtin_amdgcn_s_setprio(0); } while (0)
; #define PG8_WAIT_V(n) asm volatile("s_waitcnt vmcnt(" #n ")" ::: "memory")
; #define PG8_WAIT_L(n) asm volatile("s_waitcnt lgkmcnt(" #n ")" ::: "memory")
; #define PG8_BAR __builtin_amdgcn_s_barrier()
; #define PG8_SCHED __builtin_amdgcn_sched_barrier(0)
; template <class Epi>
; __device__ __forceinline__ void gemm_phase(LAS unsigned char* lds, const Gemm g, const StaticOrder& S, const Epi& E, const int wid) {
;     ...
;         for (int t = 0; t < nt; t += 2) {
;             const bool last = (t == nt - 2);
;             const char* a1 = cA + (size_t)(t + 1) * kstep;
;             const char* a2 = last ? nA : cA + (size_t)(t + 2) * kstep; const char* b2 = last ? nB : cB + (size_t)(t + 2) * kstep;
;             const char* a3 = a2 + kstep; const char* b3 = b2 + kstep;
;             PG8_LDB(B0, 0, 0); PG8_LDB(B1, 0, 1); PG8_SCHED; PG8_LDA(At, 0, 0); PG8_STAGE(PG8_SA(1, 1), a1 + hstepA, voffA);
;             PG8_WAIT_V(8); PG8_WAIT_L(0); PG8_BAR; PG8_MMA(0, 0, At, B0); PG8_MMA(0, 1, At, B1); PG8_BAR; PG8_SCHED;
;             PG8_LDA(At, 0, 1); PG8_STAGE(PG8_SB(0, 0), b2, voffB); PG8_STAGE(PG8_SB(0, 1), b2 + hstepB, voffB); PG8_STAGE(PG8_SA(0, 0), a2, voffA);
;             PG8_WAIT_V(8); PG8_WAIT_L(0); PG8_BAR; PG8_MMA(1, 0, At, B0); PG8_MMA(1, 1, At, B1); PG8_BAR; PG8_SCHED;
.LBB0_1810:
	ds_read_b128 v[144:147], v153
	ds_read_b128 v[156:159], v153 offset:1024
	ds_read_b128 v[160:163], v153 offset:2048
	ds_read_b128 v[164:167], v153 offset:3072
	ds_read_b128 v[168:171], v154
	ds_read_b128 v[172:175], v154 offset:1024
	ds_read_b128 v[176:179], v154 offset:2048
	ds_read_b128 v[180:183], v154 offset:3072
	s_add_u32 s26, s20, 0x100
	s_addc_u32 s27, s21, 0
	s_cmpk_eq_i32 s45, 0x54
	s_cselect_b32 s31, s7, s27
	s_cselect_b32 s30, s6, s26
	s_cselect_b32 s29, s19, s44
	s_cselect_b32 s28, s18, s43
	s_add_i32 m0, s1, 0xc000
	s_nop 0
	global_load_lds_dwordx4 v136, s[20:21]
	s_add_i32 m0, s1, 0xe000
	s_nop 0
	global_load_lds_dwordx4 v138, s[20:21]
	ds_read_b128 v[184:187], v155
	ds_read_b128 v[188:191], v155 offset:1024
	ds_read_b128 v[192:195], v155 offset:2048
	ds_read_b128 v[196:199], v155 offset:3072
	ds_read_b128 v[200:203], v155 offset:4096
	ds_read_b128 v[204:207], v155 offset:5120
	ds_read_b128 v[208:211], v155 offset:6144
	ds_read_b128 v[212:215], v155 offset:7168
	s_waitcnt vmcnt(8)
	s_waitcnt lgkmcnt(0)
	s_barrier
	s_setprio 1
	s_waitcnt lgkmcnt(0)
	v_mfma_f32_16x16x32_bf16 v[124:127], v[144:147], v[184:187], v[124:127]
	v_mfma_f32_16x16x32_bf16 v[120:123], v[160:163], v[184:187], v[120:123]
	v_mfma_f32_16x16x32_bf16 v[116:119], v[144:147], v[192:195], v[116:119]
	v_mfma_f32_16x16x32_bf16 v[112:115], v[160:163], v[192:195], v[112:115]
	v_mfma_f32_16x16x32_bf16 v[108:111], v[144:147], v[200:203], v[108:111]
	v_mfma_f32_16x16x32_bf16 v[104:107], v[160:163], v[200:203], v[104:107]
	v_mfma_f32_16x16x32_bf16 v[100:103], v[144:147], v[208:211], v[100:103]
	v_mfma_f32_16x16x32_bf16 v[96:99], v[160:163], v[208:211], v[96:99]
	v_mfma_f32_16x16x32_bf16 v[124:127], v[156:159], v[188:191], v[124:127]
	v_mfma_f32_16x16x32_bf16 v[120:123], v[164:167], v[188:191], v[120:123]
	v_mfma_f32_16x16x32_bf16 v[116:119], v[156:159], v[196:199], v[116:119]
	v_mfma_f32_16x16x32_bf16 v[112:115], v[164:167], v[196:199], v[112:115]
	v_mfma_f32_16x16x32_bf16 v[108:111], v[156:159], v[204:207], v[108:111]
	v_mfma_f32_16x16x32_bf16 v[104:107], v[164:167], v[204:207], v[104:107]
	v_mfma_f32_16x16x32_bf16 v[100:103], v[156:159], v[212:215], v[100:103]
	v_mfma_f32_16x16x32_bf16 v[96:99], v[164:167], v[212:215], v[96:99]
	s_setprio 0
	s_setprio 1
	v_mfma_f32_16x16x32_bf16 v[68:71], v[168:171], v[184:187], v[68:71]
	v_mfma_f32_16x16x32_bf16 v[64:67], v[176:179], v[184:187], v[64:67]
	v_mfma_f32_16x16x32_bf16 v[52:55], v[168:171], v[192:195], v[52:55]
	v_mfma_f32_16x16x32_bf16 v[48:51], v[176:179], v[192:195], v[48:51]
	v_mfma_f32_16x16x32_bf16 v[44:47], v[168:171], v[200:203], v[44:47]
	v_mfma_f32_16x16x32_bf16 v[40:43], v[176:179], v[200:203], v[40:43]
	v_mfma_f32_16x16x32_bf16 v[36:39], v[168:171], v[208:211], v[36:39]
	v_mfma_f32_16x16x32_bf16 v[32:35], v[176:179], v[208:211], v[32:35]
	v_mfma_f32_16x16x32_bf16 v[68:71], v[172:175], v[188:191], v[68:71]
	v_mfma_f32_16x16x32_bf16 v[64:67], v[180:183], v[188:191], v[64:67]
	v_mfma_f32_16x16x32_bf16 v[52:55], v[172:175], v[196:199], v[52:55]
	v_mfma_f32_16x16x32_bf16 v[48:51], v[180:183], v[196:199], v[48:51]
	v_mfma_f32_16x16x32_bf16 v[44:47], v[172:175], v[204:207], v[44:47]
	v_mfma_f32_16x16x32_bf16 v[40:43], v[180:183], v[204:207], v[40:43]
	v_mfma_f32_16x16x32_bf16 v[36:39], v[172:175], v[212:215], v[36:39]
	v_mfma_f32_16x16x32_bf16 v[32:35], v[180:183], v[212:215], v[32:35]
	s_setprio 0
	s_barrier
	s_add_i32 s20, s0, s94
	s_mov_b32 m0, s20
	s_nop 0
	global_load_lds_dwordx4 v132, s[28:29]
	s_add_i32 m0, s20, 0x2000
	s_add_u32 s20, s28, 0x160000
	s_addc_u32 s21, s29, 0
	s_add_i32 s24, s38, s94
	global_load_lds_dwordx4 v128, s[28:29]
	s_mov_b32 m0, s24
	s_nop 0
	global_load_lds_dwordx4 v132, s[20:21]
	s_add_i32 m0, s24, 0x2000
	s_nop 0
	global_load_lds_dwordx4 v128, s[20:21]
	s_mov_b32 m0, s1
	s_nop 0
	global_load_lds_dwordx4 v134, s[30:31]
	s_mov_b32 m0, s12
	s_nop 0
	global_load_lds_dwordx4 v130, s[30:31]
	ds_read_b128 v[184:187], v155 offset:16384
	ds_read_b128 v[188:191], v155 offset:17408
	ds_read_b128 v[192:195], v155 offset:18432
	ds_read_b128 v[196:199], v155 offset:19456
	ds_read_b128 v[200:203], v155 offset:20480
	ds_read_b128 v[204:207], v155 offset:21504
	ds_read_b128 v[208:211], v155 offset:22528
	ds_read_b128 v[212:215], v155 offset:23552
	s_waitcnt vmcnt(8)
	s_waitcnt lgkmcnt(0)
	s_barrier
	s_setprio 1
	s_waitcnt lgkmcnt(0)
	v_mfma_f32_16x16x32_bf16 v[92:95], v[144:147], v[184:187], v[92:95]
	v_mfma_f32_16x16x32_bf16 v[88:91], v[160:163], v[184:187], v[88:91]
	v_mfma_f32_16x16x32_bf16 v[84:87], v[144:147], v[192:195], v[84:87]
	v_mfma_f32_16x16x32_bf16 v[80:83], v[160:163], v[192:195], v[80:83]
	v_mfma_f32_16x16x32_bf16 v[76:79], v[144:147], v[200:203], v[76:79]
	v_mfma_f32_16x16x32_bf16 v[72:75], v[160:163], v[200:203], v[72:75]
	v_mfma_f32_16x16x32_bf16 v[60:63], v[144:147], v[208:211], v[60:63]
	v_mfma_f32_16x16x32_bf16 v[56:59], v[160:163], v[208:211], v[56:59]
	v_mfma_f32_16x16x32_bf16 v[92:95], v[156:159], v[188:191], v[92:95]
	v_mfma_f32_16x16x32_bf16 v[88:91], v[164:167], v[188:191], v[88:91]
	v_mfma_f32_16x16x32_bf16 v[84:87], v[156:159], v[196:199], v[84:87]
	v_mfma_f32_16x16x32_bf16 v[80:83], v[164:167], v[196:199], v[80:83]
	v_mfma_f32_16x16x32_bf16 v[76:79], v[156:159], v[204:207], v[76:79]
	v_mfma_f32_16x16x32_bf16 v[72:75], v[164:167], v[204:207], v[72:75]
	v_mfma_f32_16x16x32_bf16 v[60:63], v[156:159], v[212:215], v[60:63]
	v_mfma_f32_16x16x32_bf16 v[56:59], v[164:167], v[212:215], v[56:59]
	s_setprio 0
	s_setprio 1
	v_mfma_f32_16x16x32_bf16 v[28:31], v[168:171], v[184:187], v[28:31]
	v_mfma_f32_16x16x32_bf16 v[24:27], v[176:179], v[184:187], v[24:27]
	v_mfma_f32_16x16x32_bf16 v[20:23], v[168:171], v[192:195], v[20:23]
	v_mfma_f32_16x16x32_bf16 v[16:19], v[176:179], v[192:195], v[16:19]
	v_mfma_f32_16x16x32_bf16 v[12:15], v[168:171], v[200:203], v[12:15]
	v_mfma_f32_16x16x32_bf16 v[8:11], v[176:179], v[200:203], v[8:11]
	v_mfma_f32_16x16x32_bf16 v[4:7], v[168:171], v[208:211], v[4:7]
	v_mfma_f32_16x16x32_bf16 v[0:3], v[176:179], v[208:211], v[0:3]
	v_mfma_f32_16x16x32_bf16 v[28:31], v[172:175], v[188:191], v[28:31]
	v_mfma_f32_16x16x32_bf16 v[24:27], v[180:183], v[188:191], v[24:27]
	v_mfma_f32_16x16x32_bf16 v[20:23], v[172:175], v[196:199], v[20:23]
	v_mfma_f32_16x16x32_bf16 v[16:19], v[180:183], v[196:199], v[16:19]
	v_mfma_f32_16x16x32_bf16 v[12:15], v[172:175], v[204:207], v[12:15]
	v_mfma_f32_16x16x32_bf16 v[8:11], v[180:183], v[204:207], v[8:11]
	v_mfma_f32_16x16x32_bf16 v[4:7], v[172:175], v[212:215], v[4:7]
	v_mfma_f32_16x16x32_bf16 v[0:3], v[180:183], v[212:215], v[0:3]
	s_setprio 0
	s_barrier
; #define PG8_STAGE(bufoff, gbase, voff) do { _Pragma("unroll") for (int _i = 0; _i < 2; ++_i) \
;         __builtin_amdgcn_global_load_lds((const unsigned*)((const char*)(gbase) + (voff)[_i]), (LAS unsigned*)(lds + (bufoff) + ldsw + _i * 8192), 16, 0, 0); } while (0)
; #define PG8_LDA(dst, b, h) do { _Pragma("unroll") for (int m = 0; m < 4; ++m) _Pragma("unroll") for (int k = 0; k < 2; ++k) dst[m][k] = *(const LAS bf16x8*)(lds + PG8_SA(b, h) + aoff + m * 2048 + k * 1024); } while (0)
; #define PG8_LDB(dst, b, h) do { _Pragma("unroll") for (int n = 0; n < 2; ++n) _Pragma("unroll") for (int k = 0; k < 2; ++k) dst[n][k] = *(const LAS bf16x8*)(lds + PG8_SB(b, h) + boff + n * 2048 + k * 1024); } while (0)
; #define PG8_MMA(ai, bj, At, Bt) do { __builtin_amdgcn_s_setprio(1); _Pragma("unroll") for (int m = 0; m < 4; ++m) _Pragma("unroll") for (int n = 0; n < 2; ++n) _Pragma("unroll") for (int k = 0; k < 2; ++k) \
;         acc[ai][bj][m][n] = __builtin_amdgcn_mfma_f32_16x16x32_bf16(Bt[n][k], At[m][k], acc[ai][bj][m][n], 0, 0, 0); __builtin_amdgcn_s_setprio(0); } while (0)
; #define PG8_WAIT_V(n) asm volatile("s_waitcnt vmcnt(" #n ")" ::: "memory")
; #define PG8_WAIT_L(n) asm volatile("s_waitcnt lgkmcnt(" #n ")" ::: "memory")
; #define PG8_BAR __builtin_amdgcn_s_barrier()
; #define PG8_SCHED __builtin_amdgcn_sched_barrier(0)
; template <class Epi>
; __device__ __forceinline__ void gemm_phase(LAS unsigned char* lds, const Gemm g, const StaticOrder& S, const Epi& E, const int wid) {
;     ...
;             PG8_LDB(B0, 1, 0); PG8_LDB(B1, 1, 1); PG8_SCHED; PG8_LDA(At, 1, 0); PG8_STAGE(PG8_SA(0, 1), a2 + hstepA, voffA);
;             PG8_WAIT_V(8); PG8_WAIT_L(0); PG8_BAR; PG8_MMA(0, 0, At, B0); PG8_MMA(0, 1, At, B1); PG8_BAR; PG8_SCHED;
;             PG8_LDA(At, 1, 1); PG8_STAGE(PG8_SB(1, 0), b3, voffB); PG8_STAGE(PG8_SB(1, 1), b3 + hstepB, voffB); PG8_STAGE(PG8_SA(1, 0), a3, voffA);
;             PG8_WAIT_V(8); PG8_WAIT_L(0); PG8_BAR; PG8_MMA(1, 0, At, B0); PG8_MMA(1, 1, At, B1); PG8_BAR; PG8_SCHED;
;         }
	s_add_i32 s24, 0, 0x18000
	s_add_i32 s25, 0, 0x1c000
	v_add_u32_e32 v164, s24, v150
	v_add_u32_e32 v180, s25, v150
	ds_read_b128 v[144:147], v164
	ds_read_b128 v[156:159], v164 offset:1024
	ds_read_b128 v[160:163], v164 offset:2048
	ds_read_b128 v[164:167], v164 offset:3072
	ds_read_b128 v[168:171], v180
	ds_read_b128 v[172:175], v180 offset:1024
	ds_read_b128 v[176:179], v180 offset:2048
	ds_read_b128 v[180:183], v180 offset:3072
	s_add_u32 s20, s30, 0x160000
	s_addc_u32 s21, s31, 0
	s_mov_b32 m0, s15
	s_nop 0
	global_load_lds_dwordx4 v134, s[20:21]
	s_mov_b32 m0, s34
	s_nop 0
	global_load_lds_dwordx4 v130, s[20:21]
	ds_read_b128 v[184:187], v155 offset:32768
	ds_read_b128 v[188:191], v155 offset:33792
	ds_read_b128 v[192:195], v155 offset:34816
	ds_read_b128 v[196:199], v155 offset:35840
	ds_read_b128 v[200:203], v155 offset:36864
	ds_read_b128 v[204:207], v155 offset:37888
	ds_read_b128 v[208:211], v155 offset:38912
	ds_read_b128 v[212:215], v155 offset:39936
	s_waitcnt vmcnt(8)
	s_waitcnt lgkmcnt(0)
	s_barrier
	s_setprio 1
	s_waitcnt lgkmcnt(0)
	v_mfma_f32_16x16x32_bf16 v[124:127], v[144:147], v[184:187], v[124:127]
	v_mfma_f32_16x16x32_bf16 v[120:123], v[160:163], v[184:187], v[120:123]
	v_mfma_f32_16x16x32_bf16 v[116:119], v[144:147], v[192:195], v[116:119]
	v_mfma_f32_16x16x32_bf16 v[112:115], v[160:163], v[192:195], v[112:115]
	v_mfma_f32_16x16x32_bf16 v[108:111], v[144:147], v[200:203], v[108:111]
	v_mfma_f32_16x16x32_bf16 v[104:107], v[160:163], v[200:203], v[104:107]
	v_mfma_f32_16x16x32_bf16 v[100:103], v[144:147], v[208:211], v[100:103]
	v_mfma_f32_16x16x32_bf16 v[96:99], v[160:163], v[208:211], v[96:99]
	v_mfma_f32_16x16x32_bf16 v[124:127], v[156:159], v[188:191], v[124:127]
	v_mfma_f32_16x16x32_bf16 v[120:123], v[164:167], v[188:191], v[120:123]
	v_mfma_f32_16x16x32_bf16 v[116:119], v[156:159], v[196:199], v[116:119]
	v_mfma_f32_16x16x32_bf16 v[112:115], v[164:167], v[196:199], v[112:115]
	v_mfma_f32_16x16x32_bf16 v[108:111], v[156:159], v[204:207], v[108:111]
	v_mfma_f32_16x16x32_bf16 v[104:107], v[164:167], v[204:207], v[104:107]
	v_mfma_f32_16x16x32_bf16 v[100:103], v[156:159], v[212:215], v[100:103]
	v_mfma_f32_16x16x32_bf16 v[96:99], v[164:167], v[212:215], v[96:99]
	s_setprio 0
	s_setprio 1
	v_mfma_f32_16x16x32_bf16 v[68:71], v[168:171], v[184:187], v[68:71]
	v_mfma_f32_16x16x32_bf16 v[64:67], v[176:179], v[184:187], v[64:67]
	v_mfma_f32_16x16x32_bf16 v[52:55], v[168:171], v[192:195], v[52:55]
	v_mfma_f32_16x16x32_bf16 v[48:51], v[176:179], v[192:195], v[48:51]
	v_mfma_f32_16x16x32_bf16 v[44:47], v[168:171], v[200:203], v[44:47]
	v_mfma_f32_16x16x32_bf16 v[40:43], v[176:179], v[200:203], v[40:43]
	v_mfma_f32_16x16x32_bf16 v[36:39], v[168:171], v[208:211], v[36:39]
	v_mfma_f32_16x16x32_bf16 v[32:35], v[176:179], v[208:211], v[32:35]
	v_mfma_f32_16x16x32_bf16 v[68:71], v[172:175], v[188:191], v[68:71]
	v_mfma_f32_16x16x32_bf16 v[64:67], v[180:183], v[188:191], v[64:67]
	v_mfma_f32_16x16x32_bf16 v[52:55], v[172:175], v[196:199], v[52:55]
	v_mfma_f32_16x16x32_bf16 v[48:51], v[180:183], v[196:199], v[48:51]
	v_mfma_f32_16x16x32_bf16 v[44:47], v[172:175], v[204:207], v[44:47]
	v_mfma_f32_16x16x32_bf16 v[40:43], v[180:183], v[204:207], v[40:43]
	v_mfma_f32_16x16x32_bf16 v[36:39], v[172:175], v[212:215], v[36:39]
	v_mfma_f32_16x16x32_bf16 v[32:35], v[180:183], v[212:215], v[32:35]
	s_setprio 0
	s_barrier
	s_add_i32 s20, s24, s94
	s_add_u32 s98, s28, 0x80
	s_addc_u32 s99, s29, 0
	s_mov_b32 m0, s20
	s_nop 0
	global_load_lds_dwordx4 v132, s[98:99]
	s_add_i32 m0, s20, 0x2000
	s_add_u32 s20, s28, 0x160080
	s_addc_u32 s21, s29, 0
	s_add_i32 s24, s25, s94
	global_load_lds_dwordx4 v128, s[98:99]
	s_mov_b32 m0, s24
	s_nop 0
	global_load_lds_dwordx4 v132, s[20:21]
	s_add_i32 m0, s24, 0x2000
	s_nop 0
	global_load_lds_dwordx4 v128, s[20:21]
	s_add_u32 s100, s30, 0x80
	s_addc_u32 s101, s31, 0
	s_mov_b32 m0, s36
	s_nop 0
	global_load_lds_dwordx4 v134, s[100:101]
	s_mov_b32 m0, s37
	s_nop 0
	global_load_lds_dwordx4 v130, s[100:101]
	ds_read_b128 v[184:187], v155 offset:49152
	ds_read_b128 v[188:191], v155 offset:50176
	ds_read_b128 v[192:195], v155 offset:51200
	ds_read_b128 v[196:199], v155 offset:52224
	ds_read_b128 v[200:203], v155 offset:53248
	ds_read_b128 v[204:207], v155 offset:54272
	ds_read_b128 v[208:211], v155 offset:55296
	ds_read_b128 v[212:215], v155 offset:56320
	s_waitcnt vmcnt(8)
	s_waitcnt lgkmcnt(0)
	s_barrier
	s_setprio 1
	s_waitcnt lgkmcnt(0)
	v_mfma_f32_16x16x32_bf16 v[92:95], v[144:147], v[184:187], v[92:95]
	v_mfma_f32_16x16x32_bf16 v[88:91], v[160:163], v[184:187], v[88:91]
	v_mfma_f32_16x16x32_bf16 v[84:87], v[144:147], v[192:195], v[84:87]
	v_mfma_f32_16x16x32_bf16 v[80:83], v[160:163], v[192:195], v[80:83]
	v_mfma_f32_16x16x32_bf16 v[76:79], v[144:147], v[200:203], v[76:79]
	v_mfma_f32_16x16x32_bf16 v[72:75], v[160:163], v[200:203], v[72:75]
	v_mfma_f32_16x16x32_bf16 v[60:63], v[144:147], v[208:211], v[60:63]
	v_mfma_f32_16x16x32_bf16 v[56:59], v[160:163], v[208:211], v[56:59]
	v_mfma_f32_16x16x32_bf16 v[92:95], v[156:159], v[188:191], v[92:95]
	v_mfma_f32_16x16x32_bf16 v[88:91], v[164:167], v[188:191], v[88:91]
	v_mfma_f32_16x16x32_bf16 v[84:87], v[156:159], v[196:199], v[84:87]
	v_mfma_f32_16x16x32_bf16 v[80:83], v[164:167], v[196:199], v[80:83]
	v_mfma_f32_16x16x32_bf16 v[76:79], v[156:159], v[204:207], v[76:79]
	v_mfma_f32_16x16x32_bf16 v[72:75], v[164:167], v[204:207], v[72:75]
	v_mfma_f32_16x16x32_bf16 v[60:63], v[156:159], v[212:215], v[60:63]
	v_mfma_f32_16x16x32_bf16 v[56:59], v[164:167], v[212:215], v[56:59]
	s_setprio 0
	s_setprio 1
	v_mfma_f32_16x16x32_bf16 v[28:31], v[168:171], v[184:187], v[28:31]
	v_mfma_f32_16x16x32_bf16 v[24:27], v[176:179], v[184:187], v[24:27]
	v_mfma_f32_16x16x32_bf16 v[20:23], v[168:171], v[192:195], v[20:23]
	v_mfma_f32_16x16x32_bf16 v[16:19], v[176:179], v[192:195], v[16:19]
	v_mfma_f32_16x16x32_bf16 v[12:15], v[168:171], v[200:203], v[12:15]
	v_mfma_f32_16x16x32_bf16 v[8:11], v[176:179], v[200:203], v[8:11]
	v_mfma_f32_16x16x32_bf16 v[4:7], v[168:171], v[208:211], v[4:7]
	v_mfma_f32_16x16x32_bf16 v[0:3], v[176:179], v[208:211], v[0:3]
	v_mfma_f32_16x16x32_bf16 v[28:31], v[172:175], v[188:191], v[28:31]
	v_mfma_f32_16x16x32_bf16 v[24:27], v[180:183], v[188:191], v[24:27]
	v_mfma_f32_16x16x32_bf16 v[20:23], v[172:175], v[196:199], v[20:23]
	v_mfma_f32_16x16x32_bf16 v[16:19], v[180:183], v[196:199], v[16:19]
	v_mfma_f32_16x16x32_bf16 v[12:15], v[172:175], v[204:207], v[12:15]
	v_mfma_f32_16x16x32_bf16 v[8:11], v[180:183], v[204:207], v[8:11]
	v_mfma_f32_16x16x32_bf16 v[4:7], v[172:175], v[212:215], v[4:7]
	v_mfma_f32_16x16x32_bf16 v[0:3], v[180:183], v[212:215], v[0:3]
	s_setprio 0
	s_barrier
	s_add_i32 s45, s45, 2
	s_add_u32 s43, s43, 0x100
	s_addc_u32 s44, s44, 0
	s_cmpk_gt_u32 s45, 0x55
	s_mov_b64 s[20:21], s[26:27]
	s_cbranch_scc0 .LBB0_1810
	s_and_b64 vcc, exec, s[22:23]
	s_cbranch_vccz .LBB0_1813
	s_barrier
